# GEMM K-loops: LDS-DMA loads use SGPR base + 32-bit lane offset (saddr form) instead of a 64-bit VALU add per load (16 VALU per 2 K-tiles removed)
# speedup vs baseline: 1.0014x; 1.0014x over previous
; #define PG8_STAGE(bufoff, gbase, voff) do { _Pragma("unroll") for (int _i = 0; _i < 2; ++_i) \
;         __builtin_amdgcn_global_load_lds((const unsigned*)((const char*)(gbase) + (voff)[_i]), (PG8_LAS unsigned*)(lds + (bufoff) + ldsw + _i * 8192), 16, 0, 0); } while (0)
; #define PG8_LDA(dst, b, h) do { _Pragma("unroll") for (int m = 0; m < 4; ++m) _Pragma("unroll") for (int k = 0; k < 2; ++k) dst[m][k] = *(const PG8_LAS bf16x8*)(lds + PG8_SA(b, h) + aoff + m * 2048 + k * 1024); } while (0)
; #define PG8_LDB(dst, b, h) do { _Pragma("unroll") for (int n = 0; n < 2; ++n) _Pragma("unroll") for (int k = 0; k < 2; ++k) dst[n][k] = *(const PG8_LAS bf16x8*)(lds + PG8_SB(b, h) + boff + n * 2048 + k * 1024); } while (0)
; #define PG8_MMA(ai, bj, At, Bt) do { __builtin_amdgcn_s_setprio(1); _Pragma("unroll") for (int m = 0; m < 4; ++m) _Pragma("unroll") for (int n = 0; n < 2; ++n) _Pragma("unroll") for (int k = 0; k < 2; ++k) \
;         acc[ai][bj][m][n] = __builtin_amdgcn_mfma_f32_16x16x32_bf16(Bt[n][k], At[m][k], acc[ai][bj][m][n], 0, 0, 0); __builtin_amdgcn_s_setprio(0); } while (0)
; #define PG8_WAIT_V(n) asm volatile("s_waitcnt vmcnt(" #n ")" ::: "memory")
; #define PG8_WAIT_L(n) asm volatile("s_waitcnt lgkmcnt(" #n ")" ::: "memory")
; #define PG8_BAR __builtin_amdgcn_s_barrier()
; #define PG8_SCHED __builtin_amdgcn_sched_barrier(0)
; template <class Epi, class Sched, bool ALIGN_EPI = false, bool SP2 = false>
; __device__ __forceinline__ void gemm_phase(PG8_LAS unsigned char* lds, const Gemm g, const Sched& S, const Epi& E, const int wave0) {
;     ...
;             PG8_LDB(B0, 0, 0); PG8_LDB(B1, 0, 1); PG8_SCHED; PG8_LDA(At, 0, 0); PG8_STAGE(PG8_SA(1, 1), a1 + hstep, voffA);
;             PG8_WAIT_V(8); PG8_WAIT_L(0); PG8_BAR; PG8_MMA(0, 0, At, B0); PG8_MMA(0, 1, At, B1); PG8_BAR; PG8_SCHED;
;             PG8_LDA(At, 0, 1); PG8_STAGE(PG8_SB(0, 0), b2, voffB); PG8_STAGE(PG8_SB(0, 1), b2 + hstep, voffB); PG8_STAGE(PG8_SA(0, 0), a2, voffA);
;             PG8_WAIT_V(8); PG8_WAIT_L(0); PG8_BAR; PG8_MMA(1, 0, At, B0); PG8_MMA(1, 1, At, B1); PG8_BAR; PG8_SCHED;
.LBB0_1024:
	s_add_u32 s8, s10, 0x100
	s_addc_u32 s9, s11, 0
	s_add_i32 s18, 0, 0x10000
	s_cmp_eq_u32 s59, 40
	s_cselect_b32 s51, s45, s9
	s_cselect_b32 s50, s44, s8
	s_cselect_b32 s49, s47, s58
	s_cselect_b32 s48, s46, s57
	s_add_i32 s19, 0, 0x14000
	v_add_u32_e32 v140, s18, v247
	v_add_u32_e32 v156, s19, v247
	ds_read_b128 v[64:67], v140
	ds_read_b128 v[68:71], v140 offset:1024
	ds_read_b128 v[136:139], v140 offset:2048
	ds_read_b128 v[140:143], v140 offset:3072
	ds_read_b128 v[144:147], v156
	ds_read_b128 v[148:151], v156 offset:1024
	ds_read_b128 v[152:155], v156 offset:2048
	ds_read_b128 v[156:159], v156 offset:3072
	s_add_i32 m0, s33, 0xc000
	ds_read_b128 v[160:163], v245
	ds_read_b128 v[164:167], v245 offset:1024
	ds_read_b128 v[168:171], v245 offset:2048
	ds_read_b128 v[172:175], v245 offset:3072
	ds_read_b128 v[176:179], v245 offset:4096
	ds_read_b128 v[180:183], v245 offset:5120
	ds_read_b128 v[184:187], v245 offset:6144
	ds_read_b128 v[188:191], v245 offset:7168
	global_load_lds_dwordx4 v224, s[10:11]
	s_add_i32 m0, s33, 0xe000
	s_nop 0
	global_load_lds_dwordx4 v226, s[10:11]
	s_waitcnt vmcnt(8)
	s_waitcnt lgkmcnt(0)
	s_barrier
	s_setprio 1
	s_waitcnt lgkmcnt(0)
	v_mfma_f32_16x16x32_bf16 v[132:135], v[64:67], v[160:163], v[132:135]
	v_mfma_f32_16x16x32_bf16 v[128:131], v[136:139], v[160:163], v[128:131]
	v_mfma_f32_16x16x32_bf16 v[116:119], v[64:67], v[168:171], v[116:119]
	v_mfma_f32_16x16x32_bf16 v[108:111], v[136:139], v[168:171], v[108:111]
	v_mfma_f32_16x16x32_bf16 v[100:103], v[64:67], v[176:179], v[100:103]
	v_mfma_f32_16x16x32_bf16 v[92:95], v[136:139], v[176:179], v[92:95]
	v_mfma_f32_16x16x32_bf16 v[84:87], v[64:67], v[184:187], v[84:87]
	v_mfma_f32_16x16x32_bf16 v[76:79], v[136:139], v[184:187], v[76:79]
	v_mfma_f32_16x16x32_bf16 v[132:135], v[68:71], v[164:167], v[132:135]
	v_mfma_f32_16x16x32_bf16 v[128:131], v[140:143], v[164:167], v[128:131]
	v_mfma_f32_16x16x32_bf16 v[116:119], v[68:71], v[172:175], v[116:119]
	v_mfma_f32_16x16x32_bf16 v[108:111], v[140:143], v[172:175], v[108:111]
	v_mfma_f32_16x16x32_bf16 v[100:103], v[68:71], v[180:183], v[100:103]
	v_mfma_f32_16x16x32_bf16 v[92:95], v[140:143], v[180:183], v[92:95]
	v_mfma_f32_16x16x32_bf16 v[84:87], v[68:71], v[188:191], v[84:87]
	v_mfma_f32_16x16x32_bf16 v[76:79], v[140:143], v[188:191], v[76:79]
	s_setprio 0
	s_setprio 1
	v_mfma_f32_16x16x32_bf16 v[124:127], v[144:147], v[160:163], v[124:127]
	v_mfma_f32_16x16x32_bf16 v[120:123], v[152:155], v[160:163], v[120:123]
	v_mfma_f32_16x16x32_bf16 v[112:115], v[144:147], v[168:171], v[112:115]
	v_mfma_f32_16x16x32_bf16 v[104:107], v[152:155], v[168:171], v[104:107]
	v_mfma_f32_16x16x32_bf16 v[96:99], v[144:147], v[176:179], v[96:99]
	v_mfma_f32_16x16x32_bf16 v[88:91], v[152:155], v[176:179], v[88:91]
	v_mfma_f32_16x16x32_bf16 v[80:83], v[144:147], v[184:187], v[80:83]
	v_mfma_f32_16x16x32_bf16 v[72:75], v[152:155], v[184:187], v[72:75]
	v_mfma_f32_16x16x32_bf16 v[124:127], v[148:151], v[164:167], v[124:127]
	v_mfma_f32_16x16x32_bf16 v[120:123], v[156:159], v[164:167], v[120:123]
	v_mfma_f32_16x16x32_bf16 v[112:115], v[148:151], v[172:175], v[112:115]
	v_mfma_f32_16x16x32_bf16 v[104:107], v[156:159], v[172:175], v[104:107]
	v_mfma_f32_16x16x32_bf16 v[96:99], v[148:151], v[180:183], v[96:99]
	v_mfma_f32_16x16x32_bf16 v[88:91], v[156:159], v[180:183], v[88:91]
	v_mfma_f32_16x16x32_bf16 v[80:83], v[148:151], v[188:191], v[80:83]
	v_mfma_f32_16x16x32_bf16 v[72:75], v[156:159], v[188:191], v[72:75]
	s_setprio 0
	s_barrier
	s_add_i32 s10, s18, s95
	s_mov_b32 m0, s10
	ds_read_b128 v[160:163], v245 offset:16384
	ds_read_b128 v[164:167], v245 offset:17408
	ds_read_b128 v[168:171], v245 offset:18432
	ds_read_b128 v[172:175], v245 offset:19456
	ds_read_b128 v[176:179], v245 offset:20480
	ds_read_b128 v[180:183], v245 offset:21504
	ds_read_b128 v[184:187], v245 offset:22528
	ds_read_b128 v[188:191], v245 offset:23552
	global_load_lds_dwordx4 v218, s[48:49]
	s_add_i32 m0, s10, 0x2000
	s_add_u32 s10, s48, 0xb0000
	s_addc_u32 s11, s49, 0
	s_add_i32 s18, s19, s95
	global_load_lds_dwordx4 v222, s[48:49]
	s_mov_b32 m0, s18
	s_nop 0
	global_load_lds_dwordx4 v218, s[10:11]
	s_add_i32 m0, s18, 0x2000
	s_nop 0
	global_load_lds_dwordx4 v222, s[10:11]
	s_mov_b32 m0, s33
	s_nop 0
	global_load_lds_dwordx4 v216, s[50:51]
	s_mov_b32 m0, s82
	s_nop 0
	global_load_lds_dwordx4 v220, s[50:51]
	s_waitcnt vmcnt(8)
	s_waitcnt lgkmcnt(0)
	s_barrier
	s_setprio 1
	s_waitcnt lgkmcnt(0)
	v_mfma_f32_16x16x32_bf16 v[60:63], v[64:67], v[160:163], v[60:63]
	v_mfma_f32_16x16x32_bf16 v[52:55], v[136:139], v[160:163], v[52:55]
	v_mfma_f32_16x16x32_bf16 v[44:47], v[64:67], v[168:171], v[44:47]
	v_mfma_f32_16x16x32_bf16 v[36:39], v[136:139], v[168:171], v[36:39]
	v_mfma_f32_16x16x32_bf16 v[28:31], v[64:67], v[176:179], v[28:31]
	v_mfma_f32_16x16x32_bf16 v[20:23], v[136:139], v[176:179], v[20:23]
	v_mfma_f32_16x16x32_bf16 v[12:15], v[64:67], v[184:187], v[12:15]
	v_mfma_f32_16x16x32_bf16 v[4:7], v[136:139], v[184:187], v[4:7]
	v_mfma_f32_16x16x32_bf16 v[60:63], v[68:71], v[164:167], v[60:63]
	v_mfma_f32_16x16x32_bf16 v[52:55], v[140:143], v[164:167], v[52:55]
	v_mfma_f32_16x16x32_bf16 v[44:47], v[68:71], v[172:175], v[44:47]
	v_mfma_f32_16x16x32_bf16 v[36:39], v[140:143], v[172:175], v[36:39]
	v_mfma_f32_16x16x32_bf16 v[28:31], v[68:71], v[180:183], v[28:31]
	v_mfma_f32_16x16x32_bf16 v[20:23], v[140:143], v[180:183], v[20:23]
	v_mfma_f32_16x16x32_bf16 v[12:15], v[68:71], v[188:191], v[12:15]
	v_mfma_f32_16x16x32_bf16 v[4:7], v[140:143], v[188:191], v[4:7]
	s_setprio 0
	s_setprio 1
	v_mfma_f32_16x16x32_bf16 v[56:59], v[144:147], v[160:163], v[56:59]
	v_mfma_f32_16x16x32_bf16 v[48:51], v[152:155], v[160:163], v[48:51]
	v_mfma_f32_16x16x32_bf16 v[40:43], v[144:147], v[168:171], v[40:43]
	v_mfma_f32_16x16x32_bf16 v[32:35], v[152:155], v[168:171], v[32:35]
	v_mfma_f32_16x16x32_bf16 v[24:27], v[144:147], v[176:179], v[24:27]
	v_mfma_f32_16x16x32_bf16 v[16:19], v[152:155], v[176:179], v[16:19]
	v_mfma_f32_16x16x32_bf16 v[8:11], v[144:147], v[184:187], v[8:11]
	v_mfma_f32_16x16x32_bf16 v[0:3], v[152:155], v[184:187], v[0:3]
	v_mfma_f32_16x16x32_bf16 v[56:59], v[148:151], v[164:167], v[56:59]
	v_mfma_f32_16x16x32_bf16 v[48:51], v[156:159], v[164:167], v[48:51]
	v_mfma_f32_16x16x32_bf16 v[40:43], v[148:151], v[172:175], v[40:43]
	v_mfma_f32_16x16x32_bf16 v[32:35], v[156:159], v[172:175], v[32:35]
	v_mfma_f32_16x16x32_bf16 v[24:27], v[148:151], v[180:183], v[24:27]
	v_mfma_f32_16x16x32_bf16 v[16:19], v[156:159], v[180:183], v[16:19]
	v_mfma_f32_16x16x32_bf16 v[8:11], v[148:151], v[188:191], v[8:11]
	v_mfma_f32_16x16x32_bf16 v[0:3], v[156:159], v[188:191], v[0:3]
	s_setprio 0
	s_barrier
; #define PG8_STAGE(bufoff, gbase, voff) do { _Pragma("unroll") for (int _i = 0; _i < 2; ++_i) \
;         __builtin_amdgcn_global_load_lds((const unsigned*)((const char*)(gbase) + (voff)[_i]), (PG8_LAS unsigned*)(lds + (bufoff) + ldsw + _i * 8192), 16, 0, 0); } while (0)
; #define PG8_LDA(dst, b, h) do { _Pragma("unroll") for (int m = 0; m < 4; ++m) _Pragma("unroll") for (int k = 0; k < 2; ++k) dst[m][k] = *(const PG8_LAS bf16x8*)(lds + PG8_SA(b, h) + aoff + m * 2048 + k * 1024); } while (0)
; #define PG8_LDB(dst, b, h) do { _Pragma("unroll") for (int n = 0; n < 2; ++n) _Pragma("unroll") for (int k = 0; k < 2; ++k) dst[n][k] = *(const PG8_LAS bf16x8*)(lds + PG8_SB(b, h) + boff + n * 2048 + k * 1024); } while (0)
; #define PG8_MMA(ai, bj, At, Bt) do { __builtin_amdgcn_s_setprio(1); _Pragma("unroll") for (int m = 0; m < 4; ++m) _Pragma("unroll") for (int n = 0; n < 2; ++n) _Pragma("unroll") for (int k = 0; k < 2; ++k) \
;         acc[ai][bj][m][n] = __builtin_amdgcn_mfma_f32_16x16x32_bf16(Bt[n][k], At[m][k], acc[ai][bj][m][n], 0, 0, 0); __builtin_amdgcn_s_setprio(0); } while (0)
; #define PG8_WAIT_V(n) asm volatile("s_waitcnt vmcnt(" #n ")" ::: "memory")
; #define PG8_WAIT_L(n) asm volatile("s_waitcnt lgkmcnt(" #n ")" ::: "memory")
; #define PG8_BAR __builtin_amdgcn_s_barrier()
; #define PG8_SCHED __builtin_amdgcn_sched_barrier(0)
; template <class Epi, class Sched, bool ALIGN_EPI = false, bool SP2 = false>
; __device__ __forceinline__ void gemm_phase(PG8_LAS unsigned char* lds, const Gemm g, const Sched& S, const Epi& E, const int wave0) {
;     ...
;             PG8_LDB(B0, 1, 0); PG8_LDB(B1, 1, 1); PG8_SCHED; PG8_LDA(At, 1, 0); PG8_STAGE(PG8_SA(0, 1), a2 + hstep, voffA);
;             PG8_WAIT_V(8); PG8_WAIT_L(0); PG8_BAR; PG8_MMA(0, 0, At, B0); PG8_MMA(0, 1, At, B1); PG8_BAR; PG8_SCHED;
;             PG8_LDA(At, 1, 1); PG8_STAGE(PG8_SB(1, 0), b3, voffB); PG8_STAGE(PG8_SB(1, 1), b3 + hstep, voffB); PG8_STAGE(PG8_SA(1, 0), a3, voffA);
;             PG8_WAIT_V(8); PG8_WAIT_L(0); PG8_BAR; PG8_MMA(1, 0, At, B0); PG8_MMA(1, 1, At, B1); PG8_BAR; PG8_SCHED;
	s_add_i32 s18, 0, 0x18000
	s_add_i32 s19, 0, 0x1c000
	v_add_u32_e32 v140, s18, v247
	v_add_u32_e32 v156, s19, v247
	ds_read_b128 v[64:67], v140
	ds_read_b128 v[68:71], v140 offset:1024
	ds_read_b128 v[136:139], v140 offset:2048
	ds_read_b128 v[140:143], v140 offset:3072
	ds_read_b128 v[144:147], v156
	ds_read_b128 v[148:151], v156 offset:1024
	ds_read_b128 v[152:155], v156 offset:2048
	ds_read_b128 v[156:159], v156 offset:3072
	s_add_u32 s10, s50, 0xb0000
	s_addc_u32 s11, s51, 0
	s_mov_b32 m0, s16
	ds_read_b128 v[160:163], v245 offset:32768
	ds_read_b128 v[164:167], v245 offset:33792
	ds_read_b128 v[168:171], v245 offset:34816
	ds_read_b128 v[172:175], v245 offset:35840
	ds_read_b128 v[176:179], v245 offset:36864
	ds_read_b128 v[180:183], v245 offset:37888
	ds_read_b128 v[184:187], v245 offset:38912
	ds_read_b128 v[188:191], v245 offset:39936
	global_load_lds_dwordx4 v216, s[10:11]
	s_mov_b32 m0, s83
	s_nop 0
	global_load_lds_dwordx4 v220, s[10:11]
	s_waitcnt vmcnt(8)
	s_waitcnt lgkmcnt(0)
	s_barrier
	s_setprio 1
	s_waitcnt lgkmcnt(0)
	v_mfma_f32_16x16x32_bf16 v[132:135], v[64:67], v[160:163], v[132:135]
	v_mfma_f32_16x16x32_bf16 v[128:131], v[136:139], v[160:163], v[128:131]
	v_mfma_f32_16x16x32_bf16 v[116:119], v[64:67], v[168:171], v[116:119]
	v_mfma_f32_16x16x32_bf16 v[108:111], v[136:139], v[168:171], v[108:111]
	v_mfma_f32_16x16x32_bf16 v[100:103], v[64:67], v[176:179], v[100:103]
	v_mfma_f32_16x16x32_bf16 v[92:95], v[136:139], v[176:179], v[92:95]
	v_mfma_f32_16x16x32_bf16 v[84:87], v[64:67], v[184:187], v[84:87]
	v_mfma_f32_16x16x32_bf16 v[76:79], v[136:139], v[184:187], v[76:79]
	v_mfma_f32_16x16x32_bf16 v[132:135], v[68:71], v[164:167], v[132:135]
	v_mfma_f32_16x16x32_bf16 v[128:131], v[140:143], v[164:167], v[128:131]
	v_mfma_f32_16x16x32_bf16 v[116:119], v[68:71], v[172:175], v[116:119]
	v_mfma_f32_16x16x32_bf16 v[108:111], v[140:143], v[172:175], v[108:111]
	v_mfma_f32_16x16x32_bf16 v[100:103], v[68:71], v[180:183], v[100:103]
	v_mfma_f32_16x16x32_bf16 v[92:95], v[140:143], v[180:183], v[92:95]
	v_mfma_f32_16x16x32_bf16 v[84:87], v[68:71], v[188:191], v[84:87]
	v_mfma_f32_16x16x32_bf16 v[76:79], v[140:143], v[188:191], v[76:79]
	s_setprio 0
	s_setprio 1
	v_mfma_f32_16x16x32_bf16 v[124:127], v[144:147], v[160:163], v[124:127]
	v_mfma_f32_16x16x32_bf16 v[120:123], v[152:155], v[160:163], v[120:123]
	v_mfma_f32_16x16x32_bf16 v[112:115], v[144:147], v[168:171], v[112:115]
	v_mfma_f32_16x16x32_bf16 v[104:107], v[152:155], v[168:171], v[104:107]
	v_mfma_f32_16x16x32_bf16 v[96:99], v[144:147], v[176:179], v[96:99]
	v_mfma_f32_16x16x32_bf16 v[88:91], v[152:155], v[176:179], v[88:91]
	v_mfma_f32_16x16x32_bf16 v[80:83], v[144:147], v[184:187], v[80:83]
	v_mfma_f32_16x16x32_bf16 v[72:75], v[152:155], v[184:187], v[72:75]
	v_mfma_f32_16x16x32_bf16 v[124:127], v[148:151], v[164:167], v[124:127]
	v_mfma_f32_16x16x32_bf16 v[120:123], v[156:159], v[164:167], v[120:123]
	v_mfma_f32_16x16x32_bf16 v[112:115], v[148:151], v[172:175], v[112:115]
	v_mfma_f32_16x16x32_bf16 v[104:107], v[156:159], v[172:175], v[104:107]
	v_mfma_f32_16x16x32_bf16 v[96:99], v[148:151], v[180:183], v[96:99]
	v_mfma_f32_16x16x32_bf16 v[88:91], v[156:159], v[180:183], v[88:91]
	v_mfma_f32_16x16x32_bf16 v[80:83], v[148:151], v[188:191], v[80:83]
	v_mfma_f32_16x16x32_bf16 v[72:75], v[156:159], v[188:191], v[72:75]
	s_setprio 0
	s_barrier
	s_add_i32 s10, s18, s95
	s_add_i32 m0, s10, 0xffffff80
	ds_read_b128 v[160:163], v245 offset:49152
	ds_read_b128 v[164:167], v245 offset:50176
	ds_read_b128 v[168:171], v245 offset:51200
	ds_read_b128 v[172:175], v245 offset:52224
	ds_read_b128 v[176:179], v245 offset:53248
	ds_read_b128 v[180:183], v245 offset:54272
	ds_read_b128 v[184:187], v245 offset:55296
	ds_read_b128 v[188:191], v245 offset:56320
	global_load_lds_dwordx4 v218, s[48:49] offset:128
	s_add_i32 m0, s10, 0x1f80
	s_add_u32 s10, s48, 0xb0080
	s_addc_u32 s11, s49, 0
	s_add_i32 s18, s19, s95
	global_load_lds_dwordx4 v222, s[48:49] offset:128
	s_mov_b32 m0, s18
	s_nop 0
	global_load_lds_dwordx4 v218, s[10:11]
	s_add_i32 m0, s18, 0x2000
	s_nop 0
	global_load_lds_dwordx4 v222, s[10:11]
	s_add_i32 m0, s17, 0xffffff80
	s_nop 0
	global_load_lds_dwordx4 v216, s[50:51] offset:128
	s_add_i32 m0, s23, 0xffffff80
	s_nop 0
	global_load_lds_dwordx4 v220, s[50:51] offset:128
	s_waitcnt vmcnt(8)
	s_waitcnt lgkmcnt(0)
	s_barrier
	s_setprio 1
	s_waitcnt lgkmcnt(0)
	v_mfma_f32_16x16x32_bf16 v[60:63], v[64:67], v[160:163], v[60:63]
	v_mfma_f32_16x16x32_bf16 v[52:55], v[136:139], v[160:163], v[52:55]
	v_mfma_f32_16x16x32_bf16 v[44:47], v[64:67], v[168:171], v[44:47]
	v_mfma_f32_16x16x32_bf16 v[36:39], v[136:139], v[168:171], v[36:39]
	v_mfma_f32_16x16x32_bf16 v[28:31], v[64:67], v[176:179], v[28:31]
	v_mfma_f32_16x16x32_bf16 v[20:23], v[136:139], v[176:179], v[20:23]
	v_mfma_f32_16x16x32_bf16 v[12:15], v[64:67], v[184:187], v[12:15]
	v_mfma_f32_16x16x32_bf16 v[4:7], v[136:139], v[184:187], v[4:7]
	v_mfma_f32_16x16x32_bf16 v[60:63], v[68:71], v[164:167], v[60:63]
	v_mfma_f32_16x16x32_bf16 v[52:55], v[140:143], v[164:167], v[52:55]
	v_mfma_f32_16x16x32_bf16 v[44:47], v[68:71], v[172:175], v[44:47]
	v_mfma_f32_16x16x32_bf16 v[36:39], v[140:143], v[172:175], v[36:39]
	v_mfma_f32_16x16x32_bf16 v[28:31], v[68:71], v[180:183], v[28:31]
	v_mfma_f32_16x16x32_bf16 v[20:23], v[140:143], v[180:183], v[20:23]
	v_mfma_f32_16x16x32_bf16 v[12:15], v[68:71], v[188:191], v[12:15]
	v_mfma_f32_16x16x32_bf16 v[4:7], v[140:143], v[188:191], v[4:7]
	s_setprio 0
	s_setprio 1
	v_mfma_f32_16x16x32_bf16 v[56:59], v[144:147], v[160:163], v[56:59]
	v_mfma_f32_16x16x32_bf16 v[48:51], v[152:155], v[160:163], v[48:51]
	v_mfma_f32_16x16x32_bf16 v[40:43], v[144:147], v[168:171], v[40:43]
	v_mfma_f32_16x16x32_bf16 v[32:35], v[152:155], v[168:171], v[32:35]
	v_mfma_f32_16x16x32_bf16 v[24:27], v[144:147], v[176:179], v[24:27]
	v_mfma_f32_16x16x32_bf16 v[16:19], v[152:155], v[176:179], v[16:19]
	v_mfma_f32_16x16x32_bf16 v[8:11], v[144:147], v[184:187], v[8:11]
	v_mfma_f32_16x16x32_bf16 v[0:3], v[152:155], v[184:187], v[0:3]
	v_mfma_f32_16x16x32_bf16 v[56:59], v[148:151], v[164:167], v[56:59]
	v_mfma_f32_16x16x32_bf16 v[48:51], v[156:159], v[164:167], v[48:51]
	v_mfma_f32_16x16x32_bf16 v[40:43], v[148:151], v[172:175], v[40:43]
	v_mfma_f32_16x16x32_bf16 v[32:35], v[156:159], v[172:175], v[32:35]
	v_mfma_f32_16x16x32_bf16 v[24:27], v[148:151], v[180:183], v[24:27]
	v_mfma_f32_16x16x32_bf16 v[16:19], v[156:159], v[180:183], v[16:19]
	v_mfma_f32_16x16x32_bf16 v[8:11], v[148:151], v[188:191], v[8:11]
	v_mfma_f32_16x16x32_bf16 v[0:3], v[156:159], v[188:191], v[0:3]
	s_setprio 0
	s_barrier
	s_add_i32 s59, s59, 2
	s_add_u32 s57, s57, 0x100
	s_addc_u32 s58, s58, 0
	s_cmp_gt_u32 s59, 41
	s_mov_b64 s[10:11], s[8:9]
	s_cbranch_scc0 .LBB0_1024
	s_and_b64 vcc, exec, s[66:67]
	s_cbranch_vccz .LBB0_1027
	s_barrier

; #define PG8_STAGE(bufoff, gbase, voff) do { _Pragma("unroll") for (int _i = 0; _i < 2; ++_i) \
;         __builtin_amdgcn_global_load_lds((const unsigned*)((const char*)(gbase) + (voff)[_i]), (PG8_LAS unsigned*)(lds + (bufoff) + ldsw + _i * 8192), 16, 0, 0); } while (0)
; #define PG8_LDA(dst, b, h) do { _Pragma("unroll") for (int m = 0; m < 4; ++m) _Pragma("unroll") for (int k = 0; k < 2; ++k) dst[m][k] = *(const PG8_LAS bf16x8*)(lds + PG8_SA(b, h) + aoff + m * 2048 + k * 1024); } while (0)
; #define PG8_LDB(dst, b, h) do { _Pragma("unroll") for (int n = 0; n < 2; ++n) _Pragma("unroll") for (int k = 0; k < 2; ++k) dst[n][k] = *(const PG8_LAS bf16x8*)(lds + PG8_SB(b, h) + boff + n * 2048 + k * 1024); } while (0)
; #define PG8_MMA(ai, bj, At, Bt) do { __builtin_amdgcn_s_setprio(1); _Pragma("unroll") for (int m = 0; m < 4; ++m) _Pragma("unroll") for (int n = 0; n < 2; ++n) _Pragma("unroll") for (int k = 0; k < 2; ++k) \
;         acc[ai][bj][m][n] = __builtin_amdgcn_mfma_f32_16x16x32_bf16(Bt[n][k], At[m][k], acc[ai][bj][m][n], 0, 0, 0); __builtin_amdgcn_s_setprio(0); } while (0)
; #define PG8_WAIT_V(n) asm volatile("s_waitcnt vmcnt(" #n ")" ::: "memory")
; #define PG8_WAIT_L(n) asm volatile("s_waitcnt lgkmcnt(" #n ")" ::: "memory")
; #define PG8_BAR __builtin_amdgcn_s_barrier()
; #define PG8_SCHED __builtin_amdgcn_sched_barrier(0)
; template <class Epi, class Sched, bool ALIGN_EPI = false, bool SP2 = false>
; __device__ __forceinline__ void gemm_phase(PG8_LAS unsigned char* lds, const Gemm g, const Sched& S, const Epi& E, const int wave0) {
;     ...
;             PG8_LDB(B0, 0, 0); PG8_LDB(B1, 0, 1); PG8_SCHED; PG8_LDA(At, 0, 0); PG8_STAGE(PG8_SA(1, 1), a1 + hstep, voffA);
;             PG8_WAIT_V(8); PG8_WAIT_L(0); PG8_BAR; PG8_MMA(0, 0, At, B0); PG8_MMA(0, 1, At, B1); PG8_BAR; PG8_SCHED;
;             PG8_LDA(At, 0, 1); PG8_STAGE(PG8_SB(0, 0), b2, voffB); PG8_STAGE(PG8_SB(0, 1), b2 + hstep, voffB); PG8_STAGE(PG8_SA(0, 0), a2, voffA);
;             PG8_WAIT_V(8); PG8_WAIT_L(0); PG8_BAR; PG8_MMA(1, 0, At, B0); PG8_MMA(1, 1, At, B1); PG8_BAR; PG8_SCHED;
.LBB0_1140:
	s_add_u32 s18, s10, 0xfffc0080
	s_addc_u32 s19, s11, -1
	s_add_i32 s64, 0, 0x10000
	s_cmp_eq_u32 s63, 12
	s_cselect_b32 s59, s9, s19
	s_cselect_b32 s58, s49, s18
	s_cselect_b32 s57, s47, s62
	s_cselect_b32 s56, s60, s61
	s_add_i32 s65, 0, 0x14000
	v_add_u32_e32 v140, s64, v247
	v_add_u32_e32 v156, s65, v247
	ds_read_b128 v[64:67], v140
	ds_read_b128 v[68:71], v140 offset:1024
	ds_read_b128 v[136:139], v140 offset:2048
	ds_read_b128 v[140:143], v140 offset:3072
	ds_read_b128 v[144:147], v156
	ds_read_b128 v[148:151], v156 offset:1024
	ds_read_b128 v[152:155], v156 offset:2048
	ds_read_b128 v[156:159], v156 offset:3072
	s_add_i32 m0, s33, 0xc000
	ds_read_b128 v[160:163], v245
	ds_read_b128 v[164:167], v245 offset:1024
	ds_read_b128 v[168:171], v245 offset:2048
	ds_read_b128 v[172:175], v245 offset:3072
	ds_read_b128 v[176:179], v245 offset:4096
	ds_read_b128 v[180:183], v245 offset:5120
	ds_read_b128 v[184:187], v245 offset:6144
	ds_read_b128 v[188:191], v245 offset:7168
	global_load_lds_dwordx4 v224, s[10:11]
	s_add_i32 m0, s33, 0xe000
	s_nop 0
	global_load_lds_dwordx4 v226, s[10:11]
	s_waitcnt vmcnt(8)
	s_waitcnt lgkmcnt(0)
	s_barrier
	s_setprio 1
	s_waitcnt lgkmcnt(0)
	v_mfma_f32_16x16x32_bf16 v[132:135], v[64:67], v[160:163], v[132:135]
	v_mfma_f32_16x16x32_bf16 v[128:131], v[136:139], v[160:163], v[128:131]
	v_mfma_f32_16x16x32_bf16 v[116:119], v[64:67], v[168:171], v[116:119]
	v_mfma_f32_16x16x32_bf16 v[108:111], v[136:139], v[168:171], v[108:111]
	v_mfma_f32_16x16x32_bf16 v[100:103], v[64:67], v[176:179], v[100:103]
	v_mfma_f32_16x16x32_bf16 v[92:95], v[136:139], v[176:179], v[92:95]
	v_mfma_f32_16x16x32_bf16 v[84:87], v[64:67], v[184:187], v[84:87]
	v_mfma_f32_16x16x32_bf16 v[76:79], v[136:139], v[184:187], v[76:79]
	v_mfma_f32_16x16x32_bf16 v[132:135], v[68:71], v[164:167], v[132:135]
	v_mfma_f32_16x16x32_bf16 v[128:131], v[140:143], v[164:167], v[128:131]
	v_mfma_f32_16x16x32_bf16 v[116:119], v[68:71], v[172:175], v[116:119]
	v_mfma_f32_16x16x32_bf16 v[108:111], v[140:143], v[172:175], v[108:111]
	v_mfma_f32_16x16x32_bf16 v[100:103], v[68:71], v[180:183], v[100:103]
	v_mfma_f32_16x16x32_bf16 v[92:95], v[140:143], v[180:183], v[92:95]
	v_mfma_f32_16x16x32_bf16 v[84:87], v[68:71], v[188:191], v[84:87]
	v_mfma_f32_16x16x32_bf16 v[76:79], v[140:143], v[188:191], v[76:79]
	s_setprio 0
	s_setprio 1
	v_mfma_f32_16x16x32_bf16 v[124:127], v[144:147], v[160:163], v[124:127]
	v_mfma_f32_16x16x32_bf16 v[120:123], v[152:155], v[160:163], v[120:123]
	v_mfma_f32_16x16x32_bf16 v[112:115], v[144:147], v[168:171], v[112:115]
	v_mfma_f32_16x16x32_bf16 v[104:107], v[152:155], v[168:171], v[104:107]
	v_mfma_f32_16x16x32_bf16 v[96:99], v[144:147], v[176:179], v[96:99]
	v_mfma_f32_16x16x32_bf16 v[88:91], v[152:155], v[176:179], v[88:91]
	v_mfma_f32_16x16x32_bf16 v[80:83], v[144:147], v[184:187], v[80:83]
	v_mfma_f32_16x16x32_bf16 v[72:75], v[152:155], v[184:187], v[72:75]
	v_mfma_f32_16x16x32_bf16 v[124:127], v[148:151], v[164:167], v[124:127]
	v_mfma_f32_16x16x32_bf16 v[120:123], v[156:159], v[164:167], v[120:123]
	v_mfma_f32_16x16x32_bf16 v[112:115], v[148:151], v[172:175], v[112:115]
	v_mfma_f32_16x16x32_bf16 v[104:107], v[156:159], v[172:175], v[104:107]
	v_mfma_f32_16x16x32_bf16 v[96:99], v[148:151], v[180:183], v[96:99]
	v_mfma_f32_16x16x32_bf16 v[88:91], v[156:159], v[180:183], v[88:91]
	v_mfma_f32_16x16x32_bf16 v[80:83], v[148:151], v[188:191], v[80:83]
	v_mfma_f32_16x16x32_bf16 v[72:75], v[156:159], v[188:191], v[72:75]
	s_setprio 0
	s_barrier
	s_add_i32 s18, s64, s95
	s_mov_b32 m0, s18
	ds_read_b128 v[160:163], v245 offset:16384
	ds_read_b128 v[164:167], v245 offset:17408
	ds_read_b128 v[168:171], v245 offset:18432
	ds_read_b128 v[172:175], v245 offset:19456
	ds_read_b128 v[176:179], v245 offset:20480
	ds_read_b128 v[180:183], v245 offset:21504
	ds_read_b128 v[184:187], v245 offset:22528
	ds_read_b128 v[188:191], v245 offset:23552
	global_load_lds_dwordx4 v218, s[56:57]
	s_add_i32 m0, s18, 0x2000
	s_add_u32 s18, s56, 0x40000
	s_addc_u32 s19, s57, 0
	s_add_i32 s64, s65, s95
	global_load_lds_dwordx4 v222, s[56:57]
	s_mov_b32 m0, s64
	s_nop 0
	global_load_lds_dwordx4 v218, s[18:19]
	s_add_i32 m0, s64, 0x2000
	s_nop 0
	global_load_lds_dwordx4 v222, s[18:19]
	s_mov_b32 m0, s33
	s_nop 0
	global_load_lds_dwordx4 v216, s[58:59]
	s_mov_b32 m0, s82
	s_nop 0
	global_load_lds_dwordx4 v220, s[58:59]
	s_waitcnt vmcnt(8)
	s_waitcnt lgkmcnt(0)
	s_barrier
	s_setprio 1
	s_waitcnt lgkmcnt(0)
	v_mfma_f32_16x16x32_bf16 v[60:63], v[64:67], v[160:163], v[60:63]
	v_mfma_f32_16x16x32_bf16 v[52:55], v[136:139], v[160:163], v[52:55]
	v_mfma_f32_16x16x32_bf16 v[44:47], v[64:67], v[168:171], v[44:47]
	v_mfma_f32_16x16x32_bf16 v[36:39], v[136:139], v[168:171], v[36:39]
	v_mfma_f32_16x16x32_bf16 v[28:31], v[64:67], v[176:179], v[28:31]
	v_mfma_f32_16x16x32_bf16 v[20:23], v[136:139], v[176:179], v[20:23]
	v_mfma_f32_16x16x32_bf16 v[12:15], v[64:67], v[184:187], v[12:15]
	v_mfma_f32_16x16x32_bf16 v[4:7], v[136:139], v[184:187], v[4:7]
	v_mfma_f32_16x16x32_bf16 v[60:63], v[68:71], v[164:167], v[60:63]
	v_mfma_f32_16x16x32_bf16 v[52:55], v[140:143], v[164:167], v[52:55]
	v_mfma_f32_16x16x32_bf16 v[44:47], v[68:71], v[172:175], v[44:47]
	v_mfma_f32_16x16x32_bf16 v[36:39], v[140:143], v[172:175], v[36:39]
	v_mfma_f32_16x16x32_bf16 v[28:31], v[68:71], v[180:183], v[28:31]
	v_mfma_f32_16x16x32_bf16 v[20:23], v[140:143], v[180:183], v[20:23]
	v_mfma_f32_16x16x32_bf16 v[12:15], v[68:71], v[188:191], v[12:15]
	v_mfma_f32_16x16x32_bf16 v[4:7], v[140:143], v[188:191], v[4:7]
	s_setprio 0
	s_setprio 1
	v_mfma_f32_16x16x32_bf16 v[56:59], v[144:147], v[160:163], v[56:59]
	v_mfma_f32_16x16x32_bf16 v[48:51], v[152:155], v[160:163], v[48:51]
	v_mfma_f32_16x16x32_bf16 v[40:43], v[144:147], v[168:171], v[40:43]
	v_mfma_f32_16x16x32_bf16 v[32:35], v[152:155], v[168:171], v[32:35]
	v_mfma_f32_16x16x32_bf16 v[24:27], v[144:147], v[176:179], v[24:27]
	v_mfma_f32_16x16x32_bf16 v[16:19], v[152:155], v[176:179], v[16:19]
	v_mfma_f32_16x16x32_bf16 v[8:11], v[144:147], v[184:187], v[8:11]
	v_mfma_f32_16x16x32_bf16 v[0:3], v[152:155], v[184:187], v[0:3]
	v_mfma_f32_16x16x32_bf16 v[56:59], v[148:151], v[164:167], v[56:59]
	v_mfma_f32_16x16x32_bf16 v[48:51], v[156:159], v[164:167], v[48:51]
	v_mfma_f32_16x16x32_bf16 v[40:43], v[148:151], v[172:175], v[40:43]
	v_mfma_f32_16x16x32_bf16 v[32:35], v[156:159], v[172:175], v[32:35]
	v_mfma_f32_16x16x32_bf16 v[24:27], v[148:151], v[180:183], v[24:27]
	v_mfma_f32_16x16x32_bf16 v[16:19], v[156:159], v[180:183], v[16:19]
	v_mfma_f32_16x16x32_bf16 v[8:11], v[148:151], v[188:191], v[8:11]
	v_mfma_f32_16x16x32_bf16 v[0:3], v[156:159], v[188:191], v[0:3]
	s_setprio 0
	s_barrier
; #define PG8_STAGE(bufoff, gbase, voff) do { _Pragma("unroll") for (int _i = 0; _i < 2; ++_i) \
;         __builtin_amdgcn_global_load_lds((const unsigned*)((const char*)(gbase) + (voff)[_i]), (PG8_LAS unsigned*)(lds + (bufoff) + ldsw + _i * 8192), 16, 0, 0); } while (0)
; #define PG8_LDA(dst, b, h) do { _Pragma("unroll") for (int m = 0; m < 4; ++m) _Pragma("unroll") for (int k = 0; k < 2; ++k) dst[m][k] = *(const PG8_LAS bf16x8*)(lds + PG8_SA(b, h) + aoff + m * 2048 + k * 1024); } while (0)
; #define PG8_LDB(dst, b, h) do { _Pragma("unroll") for (int n = 0; n < 2; ++n) _Pragma("unroll") for (int k = 0; k < 2; ++k) dst[n][k] = *(const PG8_LAS bf16x8*)(lds + PG8_SB(b, h) + boff + n * 2048 + k * 1024); } while (0)
; #define PG8_MMA(ai, bj, At, Bt) do { __builtin_amdgcn_s_setprio(1); _Pragma("unroll") for (int m = 0; m < 4; ++m) _Pragma("unroll") for (int n = 0; n < 2; ++n) _Pragma("unroll") for (int k = 0; k < 2; ++k) \
;         acc[ai][bj][m][n] = __builtin_amdgcn_mfma_f32_16x16x32_bf16(Bt[n][k], At[m][k], acc[ai][bj][m][n], 0, 0, 0); __builtin_amdgcn_s_setprio(0); } while (0)
; #define PG8_WAIT_V(n) asm volatile("s_waitcnt vmcnt(" #n ")" ::: "memory")
; #define PG8_WAIT_L(n) asm volatile("s_waitcnt lgkmcnt(" #n ")" ::: "memory")
; #define PG8_BAR __builtin_amdgcn_s_barrier()
; #define PG8_SCHED __builtin_amdgcn_sched_barrier(0)
; template <class Epi, class Sched, bool ALIGN_EPI = false, bool SP2 = false>
; __device__ __forceinline__ void gemm_phase(PG8_LAS unsigned char* lds, const Gemm g, const Sched& S, const Epi& E, const int wave0) {
;     ...
;             PG8_LDB(B0, 1, 0); PG8_LDB(B1, 1, 1); PG8_SCHED; PG8_LDA(At, 1, 0); PG8_STAGE(PG8_SA(0, 1), a2 + hstep, voffA);
;             PG8_WAIT_V(8); PG8_WAIT_L(0); PG8_BAR; PG8_MMA(0, 0, At, B0); PG8_MMA(0, 1, At, B1); PG8_BAR; PG8_SCHED;
;             PG8_LDA(At, 1, 1); PG8_STAGE(PG8_SB(1, 0), b3, voffB); PG8_STAGE(PG8_SB(1, 1), b3 + hstep, voffB); PG8_STAGE(PG8_SA(1, 0), a3, voffA);
;             PG8_WAIT_V(8); PG8_WAIT_L(0); PG8_BAR; PG8_MMA(1, 0, At, B0); PG8_MMA(1, 1, At, B1); PG8_BAR; PG8_SCHED;
	s_add_i32 s64, 0, 0x18000
	s_add_i32 s65, 0, 0x1c000
	v_add_u32_e32 v140, s64, v247
	v_add_u32_e32 v156, s65, v247
	ds_read_b128 v[64:67], v140
	ds_read_b128 v[68:71], v140 offset:1024
	ds_read_b128 v[136:139], v140 offset:2048
	ds_read_b128 v[140:143], v140 offset:3072
	ds_read_b128 v[144:147], v156
	ds_read_b128 v[148:151], v156 offset:1024
	ds_read_b128 v[152:155], v156 offset:2048
	ds_read_b128 v[156:159], v156 offset:3072
	s_add_u32 s18, s58, 0x40000
	s_addc_u32 s19, s59, 0
	s_mov_b32 m0, s16
	ds_read_b128 v[160:163], v245 offset:32768
	ds_read_b128 v[164:167], v245 offset:33792
	ds_read_b128 v[168:171], v245 offset:34816
	ds_read_b128 v[172:175], v245 offset:35840
	ds_read_b128 v[176:179], v245 offset:36864
	ds_read_b128 v[180:183], v245 offset:37888
	ds_read_b128 v[184:187], v245 offset:38912
	ds_read_b128 v[188:191], v245 offset:39936
	global_load_lds_dwordx4 v216, s[18:19]
	s_mov_b32 m0, s83
	s_nop 0
	global_load_lds_dwordx4 v220, s[18:19]
	s_waitcnt vmcnt(8)
	s_waitcnt lgkmcnt(0)
	s_barrier
	s_setprio 1
	s_waitcnt lgkmcnt(0)
	v_mfma_f32_16x16x32_bf16 v[132:135], v[64:67], v[160:163], v[132:135]
	v_mfma_f32_16x16x32_bf16 v[128:131], v[136:139], v[160:163], v[128:131]
	v_mfma_f32_16x16x32_bf16 v[116:119], v[64:67], v[168:171], v[116:119]
	v_mfma_f32_16x16x32_bf16 v[108:111], v[136:139], v[168:171], v[108:111]
	v_mfma_f32_16x16x32_bf16 v[100:103], v[64:67], v[176:179], v[100:103]
	v_mfma_f32_16x16x32_bf16 v[92:95], v[136:139], v[176:179], v[92:95]
	v_mfma_f32_16x16x32_bf16 v[84:87], v[64:67], v[184:187], v[84:87]
	v_mfma_f32_16x16x32_bf16 v[76:79], v[136:139], v[184:187], v[76:79]
	v_mfma_f32_16x16x32_bf16 v[132:135], v[68:71], v[164:167], v[132:135]
	v_mfma_f32_16x16x32_bf16 v[128:131], v[140:143], v[164:167], v[128:131]
	v_mfma_f32_16x16x32_bf16 v[116:119], v[68:71], v[172:175], v[116:119]
	v_mfma_f32_16x16x32_bf16 v[108:111], v[140:143], v[172:175], v[108:111]
	v_mfma_f32_16x16x32_bf16 v[100:103], v[68:71], v[180:183], v[100:103]
	v_mfma_f32_16x16x32_bf16 v[92:95], v[140:143], v[180:183], v[92:95]
	v_mfma_f32_16x16x32_bf16 v[84:87], v[68:71], v[188:191], v[84:87]
	v_mfma_f32_16x16x32_bf16 v[76:79], v[140:143], v[188:191], v[76:79]
	s_setprio 0
	s_setprio 1
	v_mfma_f32_16x16x32_bf16 v[124:127], v[144:147], v[160:163], v[124:127]
	v_mfma_f32_16x16x32_bf16 v[120:123], v[152:155], v[160:163], v[120:123]
	v_mfma_f32_16x16x32_bf16 v[112:115], v[144:147], v[168:171], v[112:115]
	v_mfma_f32_16x16x32_bf16 v[104:107], v[152:155], v[168:171], v[104:107]
	v_mfma_f32_16x16x32_bf16 v[96:99], v[144:147], v[176:179], v[96:99]
	v_mfma_f32_16x16x32_bf16 v[88:91], v[152:155], v[176:179], v[88:91]
	v_mfma_f32_16x16x32_bf16 v[80:83], v[144:147], v[184:187], v[80:83]
	v_mfma_f32_16x16x32_bf16 v[72:75], v[152:155], v[184:187], v[72:75]
	v_mfma_f32_16x16x32_bf16 v[124:127], v[148:151], v[164:167], v[124:127]
	v_mfma_f32_16x16x32_bf16 v[120:123], v[156:159], v[164:167], v[120:123]
	v_mfma_f32_16x16x32_bf16 v[112:115], v[148:151], v[172:175], v[112:115]
	v_mfma_f32_16x16x32_bf16 v[104:107], v[156:159], v[172:175], v[104:107]
	v_mfma_f32_16x16x32_bf16 v[96:99], v[148:151], v[180:183], v[96:99]
	v_mfma_f32_16x16x32_bf16 v[88:91], v[156:159], v[180:183], v[88:91]
	v_mfma_f32_16x16x32_bf16 v[80:83], v[148:151], v[188:191], v[80:83]
	v_mfma_f32_16x16x32_bf16 v[72:75], v[156:159], v[188:191], v[72:75]
	s_setprio 0
	s_barrier
	s_add_i32 s18, s64, s95
	s_add_i32 m0, s18, 0xffffff80
	ds_read_b128 v[160:163], v245 offset:49152
	ds_read_b128 v[164:167], v245 offset:50176
	ds_read_b128 v[168:171], v245 offset:51200
	ds_read_b128 v[172:175], v245 offset:52224
	ds_read_b128 v[176:179], v245 offset:53248
	ds_read_b128 v[180:183], v245 offset:54272
	ds_read_b128 v[184:187], v245 offset:55296
	ds_read_b128 v[188:191], v245 offset:56320
	global_load_lds_dwordx4 v218, s[56:57] offset:128
	s_add_i32 m0, s18, 0x1f80
	s_add_u32 s18, s56, 0x40080
	s_addc_u32 s19, s57, 0
	global_load_lds_dwordx4 v222, s[56:57] offset:128
	s_add_i32 s56, s65, s95
	s_mov_b32 m0, s56
	s_nop 0
	global_load_lds_dwordx4 v218, s[18:19]
	s_add_i32 m0, s56, 0x2000
	s_nop 0
	global_load_lds_dwordx4 v222, s[18:19]
	s_add_i32 m0, s17, 0xffffff80
	s_nop 0
	global_load_lds_dwordx4 v216, s[58:59] offset:128
	s_add_i32 m0, s23, 0xffffff80
	s_nop 0
	global_load_lds_dwordx4 v220, s[58:59] offset:128
	s_waitcnt vmcnt(8)
	s_waitcnt lgkmcnt(0)
	s_barrier
	s_setprio 1
	s_waitcnt lgkmcnt(0)
	v_mfma_f32_16x16x32_bf16 v[60:63], v[64:67], v[160:163], v[60:63]
	v_mfma_f32_16x16x32_bf16 v[52:55], v[136:139], v[160:163], v[52:55]
	v_mfma_f32_16x16x32_bf16 v[44:47], v[64:67], v[168:171], v[44:47]
	v_mfma_f32_16x16x32_bf16 v[36:39], v[136:139], v[168:171], v[36:39]
	v_mfma_f32_16x16x32_bf16 v[28:31], v[64:67], v[176:179], v[28:31]
	v_mfma_f32_16x16x32_bf16 v[20:23], v[136:139], v[176:179], v[20:23]
	v_mfma_f32_16x16x32_bf16 v[12:15], v[64:67], v[184:187], v[12:15]
	v_mfma_f32_16x16x32_bf16 v[4:7], v[136:139], v[184:187], v[4:7]
	v_mfma_f32_16x16x32_bf16 v[60:63], v[68:71], v[164:167], v[60:63]
	v_mfma_f32_16x16x32_bf16 v[52:55], v[140:143], v[164:167], v[52:55]
	v_mfma_f32_16x16x32_bf16 v[44:47], v[68:71], v[172:175], v[44:47]
	v_mfma_f32_16x16x32_bf16 v[36:39], v[140:143], v[172:175], v[36:39]
	v_mfma_f32_16x16x32_bf16 v[28:31], v[68:71], v[180:183], v[28:31]
	v_mfma_f32_16x16x32_bf16 v[20:23], v[140:143], v[180:183], v[20:23]
	v_mfma_f32_16x16x32_bf16 v[12:15], v[68:71], v[188:191], v[12:15]
	v_mfma_f32_16x16x32_bf16 v[4:7], v[140:143], v[188:191], v[4:7]
	s_setprio 0
	s_setprio 1
	v_mfma_f32_16x16x32_bf16 v[56:59], v[144:147], v[160:163], v[56:59]
	v_mfma_f32_16x16x32_bf16 v[48:51], v[152:155], v[160:163], v[48:51]
	v_mfma_f32_16x16x32_bf16 v[40:43], v[144:147], v[168:171], v[40:43]
	v_mfma_f32_16x16x32_bf16 v[32:35], v[152:155], v[168:171], v[32:35]
	v_mfma_f32_16x16x32_bf16 v[24:27], v[144:147], v[176:179], v[24:27]
	v_mfma_f32_16x16x32_bf16 v[16:19], v[152:155], v[176:179], v[16:19]
	v_mfma_f32_16x16x32_bf16 v[8:11], v[144:147], v[184:187], v[8:11]
	v_mfma_f32_16x16x32_bf16 v[0:3], v[152:155], v[184:187], v[0:3]
	v_mfma_f32_16x16x32_bf16 v[56:59], v[148:151], v[164:167], v[56:59]
	v_mfma_f32_16x16x32_bf16 v[48:51], v[156:159], v[164:167], v[48:51]
	v_mfma_f32_16x16x32_bf16 v[40:43], v[148:151], v[172:175], v[40:43]
	v_mfma_f32_16x16x32_bf16 v[32:35], v[156:159], v[172:175], v[32:35]
	v_mfma_f32_16x16x32_bf16 v[24:27], v[148:151], v[180:183], v[24:27]
	v_mfma_f32_16x16x32_bf16 v[16:19], v[156:159], v[180:183], v[16:19]
	v_mfma_f32_16x16x32_bf16 v[8:11], v[148:151], v[188:191], v[8:11]
	v_mfma_f32_16x16x32_bf16 v[0:3], v[156:159], v[188:191], v[0:3]
	s_setprio 0
	s_barrier
	s_add_i32 s63, s63, 2
	s_add_u32 s10, s10, 0x100
	s_addc_u32 s11, s11, 0
	s_add_u32 s61, s61, 0x100
	s_addc_u32 s62, s62, 0
	s_cmp_gt_u32 s63, 13
	s_cbranch_scc0 .LBB0_1140
	s_and_b64 vcc, exec, s[66:67]
	s_cbranch_vccz .LBB0_1143
	s_barrier

; #define PG8_STAGE(bufoff, gbase, voff) do { _Pragma("unroll") for (int _i = 0; _i < 2; ++_i) \
;         __builtin_amdgcn_global_load_lds((const unsigned*)((const char*)(gbase) + (voff)[_i]), (PG8_LAS unsigned*)(lds + (bufoff) + ldsw + _i * 8192), 16, 0, 0); } while (0)
; #define PG8_LDA(dst, b, h) do { _Pragma("unroll") for (int m = 0; m < 4; ++m) _Pragma("unroll") for (int k = 0; k < 2; ++k) dst[m][k] = *(const PG8_LAS bf16x8*)(lds + PG8_SA(b, h) + aoff + m * 2048 + k * 1024); } while (0)
; #define PG8_LDB(dst, b, h) do { _Pragma("unroll") for (int n = 0; n < 2; ++n) _Pragma("unroll") for (int k = 0; k < 2; ++k) dst[n][k] = *(const PG8_LAS bf16x8*)(lds + PG8_SB(b, h) + boff + n * 2048 + k * 1024); } while (0)
; #define PG8_MMA(ai, bj, At, Bt) do { __builtin_amdgcn_s_setprio(1); _Pragma("unroll") for (int m = 0; m < 4; ++m) _Pragma("unroll") for (int n = 0; n < 2; ++n) _Pragma("unroll") for (int k = 0; k < 2; ++k) \
;         acc[ai][bj][m][n] = __builtin_amdgcn_mfma_f32_16x16x32_bf16(Bt[n][k], At[m][k], acc[ai][bj][m][n], 0, 0, 0); __builtin_amdgcn_s_setprio(0); } while (0)
; #define PG8_WAIT_V(n) asm volatile("s_waitcnt vmcnt(" #n ")" ::: "memory")
; #define PG8_WAIT_L(n) asm volatile("s_waitcnt lgkmcnt(" #n ")" ::: "memory")
; #define PG8_BAR __builtin_amdgcn_s_barrier()
; #define PG8_SCHED __builtin_amdgcn_sched_barrier(0)
; template <class Epi, class Sched, bool ALIGN_EPI = false, bool SP2 = false>
; __device__ __forceinline__ void gemm_phase(PG8_LAS unsigned char* lds, const Gemm g, const Sched& S, const Epi& E, const int wave0) {
;     ...
;             PG8_LDB(B0, 0, 0); PG8_LDB(B1, 0, 1); PG8_SCHED; PG8_LDA(At, 0, 0); PG8_STAGE(PG8_SA(1, 1), a1 + hstep, voffA);
;             PG8_WAIT_V(8); PG8_WAIT_L(0); PG8_BAR; PG8_MMA(0, 0, At, B0); PG8_MMA(0, 1, At, B1); PG8_BAR; PG8_SCHED;
;             PG8_LDA(At, 0, 1); PG8_STAGE(PG8_SB(0, 0), b2, voffB); PG8_STAGE(PG8_SB(0, 1), b2 + hstep, voffB); PG8_STAGE(PG8_SA(0, 0), a2, voffA);
;             PG8_WAIT_V(8); PG8_WAIT_L(0); PG8_BAR; PG8_MMA(1, 0, At, B0); PG8_MMA(1, 1, At, B1); PG8_BAR; PG8_SCHED;
.LBB0_1258:
	s_add_u32 s59, s12, s58
	s_addc_u32 s64, s13, 0
	s_add_u32 s60, s59, 0x100
	s_addc_u32 s61, s64, 0
	s_and_b64 s[18:19], s[56:57], exec
	s_cselect_b32 s61, s9, s61
	s_cselect_b32 s60, s17, s60
	s_add_u32 s18, s10, s58
	s_addc_u32 s19, s11, 0
	s_add_u32 s58, s18, 0x100
	s_addc_u32 s62, s19, 0
	s_add_i32 vcc_hi, 0, 0x10000
	s_and_b64 s[18:19], s[56:57], exec
	s_cselect_b32 s63, s45, s62
	s_cselect_b32 s62, s47, s58
	s_add_i32 s18, 0, 0x14000
	s_add_u32 s66, s59, 0x10080
	s_addc_u32 s67, s64, 0
	s_add_i32 s87, vcc_hi, s95
	s_add_i32 m0, s33, 0xc000
	s_add_i32 s29, s33, 0xe000
	s_add_i32 s28, s87, 0x2000
	s_add_u32 s64, s62, 0x10000
	v_add_u32_e32 v140, vcc_hi, v238
	v_add_u32_e32 v156, s18, v238
	s_addc_u32 s65, s63, 0
	s_add_i32 vcc_lo, s18, s95
	ds_read_b128 v[64:67], v140
	ds_read_b128 v[132:135], v140 offset:1024
	ds_read_b128 v[136:139], v140 offset:2048
	ds_read_b128 v[140:143], v140 offset:3072
	ds_read_b128 v[144:147], v156
	ds_read_b128 v[148:151], v156 offset:1024
	ds_read_b128 v[152:155], v156 offset:2048
	ds_read_b128 v[156:159], v156 offset:3072
	s_add_i32 s88, vcc_lo, 0x2000
	s_add_i32 s86, 0, 0x18000
	s_add_i32 s80, 0, 0x1c000
	s_add_u32 s58, s60, 0x10000
	s_addc_u32 s59, s61, 0
	s_add_i32 s74, s86, s95
	s_add_i32 s72, s74, 0x2000
	s_add_u32 s56, s62, 0x10080
	s_addc_u32 s57, s63, 0
	s_add_i32 s19, s80, s95
	s_add_i32 s18, s19, 0x2000
	ds_read_b128 v[160:163], v239
	ds_read_b128 v[164:167], v239 offset:1024
	ds_read_b128 v[168:171], v239 offset:2048
	ds_read_b128 v[172:175], v239 offset:3072
	ds_read_b128 v[176:179], v239 offset:4096
	ds_read_b128 v[180:183], v239 offset:5120
	ds_read_b128 v[184:187], v239 offset:6144
	ds_read_b128 v[188:191], v239 offset:7168
	global_load_lds_dwordx4 v216, s[66:67]
	s_mov_b32 m0, s29
	s_nop 0
	global_load_lds_dwordx4 v218, s[66:67]
	s_waitcnt vmcnt(8)
	s_waitcnt lgkmcnt(0)
	s_barrier
	s_setprio 1
	s_waitcnt lgkmcnt(0)
	v_mfma_f32_16x16x32_bf16 v[128:131], v[64:67], v[160:163], v[128:131]
	v_mfma_f32_16x16x32_bf16 v[124:127], v[136:139], v[160:163], v[124:127]
	v_mfma_f32_16x16x32_bf16 v[112:115], v[64:67], v[168:171], v[112:115]
	v_mfma_f32_16x16x32_bf16 v[104:107], v[136:139], v[168:171], v[104:107]
	v_mfma_f32_16x16x32_bf16 v[96:99], v[64:67], v[176:179], v[96:99]
	v_mfma_f32_16x16x32_bf16 v[88:91], v[136:139], v[176:179], v[88:91]
	v_mfma_f32_16x16x32_bf16 v[80:83], v[64:67], v[184:187], v[80:83]
	v_mfma_f32_16x16x32_bf16 v[72:75], v[136:139], v[184:187], v[72:75]
	v_mfma_f32_16x16x32_bf16 v[128:131], v[132:135], v[164:167], v[128:131]
	v_mfma_f32_16x16x32_bf16 v[124:127], v[140:143], v[164:167], v[124:127]
	v_mfma_f32_16x16x32_bf16 v[112:115], v[132:135], v[172:175], v[112:115]
	v_mfma_f32_16x16x32_bf16 v[104:107], v[140:143], v[172:175], v[104:107]
	v_mfma_f32_16x16x32_bf16 v[96:99], v[132:135], v[180:183], v[96:99]
	v_mfma_f32_16x16x32_bf16 v[88:91], v[140:143], v[180:183], v[88:91]
	v_mfma_f32_16x16x32_bf16 v[80:83], v[132:135], v[188:191], v[80:83]
	v_mfma_f32_16x16x32_bf16 v[72:75], v[140:143], v[188:191], v[72:75]
	s_setprio 0
	s_setprio 1
	v_mfma_f32_16x16x32_bf16 v[120:123], v[144:147], v[160:163], v[120:123]
	v_mfma_f32_16x16x32_bf16 v[116:119], v[152:155], v[160:163], v[116:119]
	v_mfma_f32_16x16x32_bf16 v[108:111], v[144:147], v[168:171], v[108:111]
	v_mfma_f32_16x16x32_bf16 v[100:103], v[152:155], v[168:171], v[100:103]
	v_mfma_f32_16x16x32_bf16 v[92:95], v[144:147], v[176:179], v[92:95]
	v_mfma_f32_16x16x32_bf16 v[84:87], v[152:155], v[176:179], v[84:87]
	v_mfma_f32_16x16x32_bf16 v[76:79], v[144:147], v[184:187], v[76:79]
	v_mfma_f32_16x16x32_bf16 v[68:71], v[152:155], v[184:187], v[68:71]
	v_mfma_f32_16x16x32_bf16 v[120:123], v[148:151], v[164:167], v[120:123]
	v_mfma_f32_16x16x32_bf16 v[116:119], v[156:159], v[164:167], v[116:119]
	v_mfma_f32_16x16x32_bf16 v[108:111], v[148:151], v[172:175], v[108:111]
	v_mfma_f32_16x16x32_bf16 v[100:103], v[156:159], v[172:175], v[100:103]
	v_mfma_f32_16x16x32_bf16 v[92:95], v[148:151], v[180:183], v[92:95]
	v_mfma_f32_16x16x32_bf16 v[84:87], v[156:159], v[180:183], v[84:87]
	v_mfma_f32_16x16x32_bf16 v[76:79], v[148:151], v[188:191], v[76:79]
	v_mfma_f32_16x16x32_bf16 v[68:71], v[156:159], v[188:191], v[68:71]
	s_setprio 0
	s_barrier
	s_mov_b32 m0, s87
	ds_read_b128 v[160:163], v239 offset:16384
	ds_read_b128 v[164:167], v239 offset:17408
	ds_read_b128 v[168:171], v239 offset:18432
	ds_read_b128 v[172:175], v239 offset:19456
	ds_read_b128 v[176:179], v239 offset:20480
	ds_read_b128 v[180:183], v239 offset:21504
	ds_read_b128 v[184:187], v239 offset:22528
	ds_read_b128 v[188:191], v239 offset:23552
	global_load_lds_dwordx4 v216, s[62:63]
	s_mov_b32 m0, s28
	s_nop 0
	global_load_lds_dwordx4 v218, s[62:63]
	s_mov_b32 m0, vcc_lo
	s_nop 0
	global_load_lds_dwordx4 v216, s[64:65]
	s_mov_b32 m0, s88
	s_nop 0
	global_load_lds_dwordx4 v218, s[64:65]
	s_mov_b32 m0, s33
	s_nop 0
	global_load_lds_dwordx4 v216, s[60:61]
	s_mov_b32 m0, s82
	s_nop 0
	global_load_lds_dwordx4 v218, s[60:61]
	s_waitcnt vmcnt(8)
	s_waitcnt lgkmcnt(0)
	s_barrier
; #define PG8_STAGE(bufoff, gbase, voff) do { _Pragma("unroll") for (int _i = 0; _i < 2; ++_i) \
;         __builtin_amdgcn_global_load_lds((const unsigned*)((const char*)(gbase) + (voff)[_i]), (PG8_LAS unsigned*)(lds + (bufoff) + ldsw + _i * 8192), 16, 0, 0); } while (0)
; #define PG8_LDA(dst, b, h) do { _Pragma("unroll") for (int m = 0; m < 4; ++m) _Pragma("unroll") for (int k = 0; k < 2; ++k) dst[m][k] = *(const PG8_LAS bf16x8*)(lds + PG8_SA(b, h) + aoff + m * 2048 + k * 1024); } while (0)
; #define PG8_LDB(dst, b, h) do { _Pragma("unroll") for (int n = 0; n < 2; ++n) _Pragma("unroll") for (int k = 0; k < 2; ++k) dst[n][k] = *(const PG8_LAS bf16x8*)(lds + PG8_SB(b, h) + boff + n * 2048 + k * 1024); } while (0)
; #define PG8_MMA(ai, bj, At, Bt) do { __builtin_amdgcn_s_setprio(1); _Pragma("unroll") for (int m = 0; m < 4; ++m) _Pragma("unroll") for (int n = 0; n < 2; ++n) _Pragma("unroll") for (int k = 0; k < 2; ++k) \
;         acc[ai][bj][m][n] = __builtin_amdgcn_mfma_f32_16x16x32_bf16(Bt[n][k], At[m][k], acc[ai][bj][m][n], 0, 0, 0); __builtin_amdgcn_s_setprio(0); } while (0)
; #define PG8_WAIT_V(n) asm volatile("s_waitcnt vmcnt(" #n ")" ::: "memory")
; #define PG8_WAIT_L(n) asm volatile("s_waitcnt lgkmcnt(" #n ")" ::: "memory")
; #define PG8_BAR __builtin_amdgcn_s_barrier()
; #define PG8_SCHED __builtin_amdgcn_sched_barrier(0)
; template <class Epi, class Sched, bool ALIGN_EPI = false, bool SP2 = false>
; __device__ __forceinline__ void gemm_phase(PG8_LAS unsigned char* lds, const Gemm g, const Sched& S, const Epi& E, const int wave0) {
;     ...
;             PG8_WAIT_V(8); PG8_WAIT_L(0); PG8_BAR; PG8_MMA(0, 0, At, B0); PG8_MMA(0, 1, At, B1); PG8_BAR; PG8_SCHED;
;             PG8_LDA(At, 0, 1); PG8_STAGE(PG8_SB(0, 0), b2, voffB); PG8_STAGE(PG8_SB(0, 1), b2 + hstep, voffB); PG8_STAGE(PG8_SA(0, 0), a2, voffA);
;             PG8_WAIT_V(8); PG8_WAIT_L(0); PG8_BAR; PG8_MMA(1, 0, At, B0); PG8_MMA(1, 1, At, B1); PG8_BAR; PG8_SCHED;
;             PG8_LDB(B0, 1, 0); PG8_LDB(B1, 1, 1); PG8_SCHED; PG8_LDA(At, 1, 0); PG8_STAGE(PG8_SA(0, 1), a2 + hstep, voffA);
;             PG8_WAIT_V(8); PG8_WAIT_L(0); PG8_BAR; PG8_MMA(0, 0, At, B0); PG8_MMA(0, 1, At, B1); PG8_BAR; PG8_SCHED;
	s_setprio 1
	s_waitcnt lgkmcnt(0)
	v_mfma_f32_16x16x32_bf16 v[60:63], v[64:67], v[160:163], v[60:63]
	v_mfma_f32_16x16x32_bf16 v[52:55], v[136:139], v[160:163], v[52:55]
	v_mfma_f32_16x16x32_bf16 v[44:47], v[64:67], v[168:171], v[44:47]
	v_mfma_f32_16x16x32_bf16 v[36:39], v[136:139], v[168:171], v[36:39]
	v_mfma_f32_16x16x32_bf16 v[28:31], v[64:67], v[176:179], v[28:31]
	v_mfma_f32_16x16x32_bf16 v[20:23], v[136:139], v[176:179], v[20:23]
	v_mfma_f32_16x16x32_bf16 v[12:15], v[64:67], v[184:187], v[12:15]
	v_mfma_f32_16x16x32_bf16 v[4:7], v[136:139], v[184:187], v[4:7]
	v_mfma_f32_16x16x32_bf16 v[60:63], v[132:135], v[164:167], v[60:63]
	v_mfma_f32_16x16x32_bf16 v[52:55], v[140:143], v[164:167], v[52:55]
	v_mfma_f32_16x16x32_bf16 v[44:47], v[132:135], v[172:175], v[44:47]
	v_mfma_f32_16x16x32_bf16 v[36:39], v[140:143], v[172:175], v[36:39]
	v_mfma_f32_16x16x32_bf16 v[28:31], v[132:135], v[180:183], v[28:31]
	v_mfma_f32_16x16x32_bf16 v[20:23], v[140:143], v[180:183], v[20:23]
	v_mfma_f32_16x16x32_bf16 v[12:15], v[132:135], v[188:191], v[12:15]
	v_mfma_f32_16x16x32_bf16 v[4:7], v[140:143], v[188:191], v[4:7]
	s_setprio 0
	s_setprio 1
	v_mfma_f32_16x16x32_bf16 v[56:59], v[144:147], v[160:163], v[56:59]
	v_mfma_f32_16x16x32_bf16 v[48:51], v[152:155], v[160:163], v[48:51]
	v_mfma_f32_16x16x32_bf16 v[40:43], v[144:147], v[168:171], v[40:43]
	v_mfma_f32_16x16x32_bf16 v[32:35], v[152:155], v[168:171], v[32:35]
	v_mfma_f32_16x16x32_bf16 v[24:27], v[144:147], v[176:179], v[24:27]
	v_mfma_f32_16x16x32_bf16 v[16:19], v[152:155], v[176:179], v[16:19]
	v_mfma_f32_16x16x32_bf16 v[8:11], v[144:147], v[184:187], v[8:11]
	v_mfma_f32_16x16x32_bf16 v[0:3], v[152:155], v[184:187], v[0:3]
	v_mfma_f32_16x16x32_bf16 v[56:59], v[148:151], v[164:167], v[56:59]
	v_mfma_f32_16x16x32_bf16 v[48:51], v[156:159], v[164:167], v[48:51]
	v_mfma_f32_16x16x32_bf16 v[40:43], v[148:151], v[172:175], v[40:43]
	v_mfma_f32_16x16x32_bf16 v[32:35], v[156:159], v[172:175], v[32:35]
	v_mfma_f32_16x16x32_bf16 v[24:27], v[148:151], v[180:183], v[24:27]
	v_mfma_f32_16x16x32_bf16 v[16:19], v[156:159], v[180:183], v[16:19]
	v_mfma_f32_16x16x32_bf16 v[8:11], v[148:151], v[188:191], v[8:11]
	v_mfma_f32_16x16x32_bf16 v[0:3], v[156:159], v[188:191], v[0:3]
	s_setprio 0
	s_barrier
	v_add_u32_e32 v140, s86, v238
	v_add_u32_e32 v156, s80, v238
	ds_read_b128 v[64:67], v140
	ds_read_b128 v[132:135], v140 offset:1024
	ds_read_b128 v[136:139], v140 offset:2048
	ds_read_b128 v[140:143], v140 offset:3072
	ds_read_b128 v[144:147], v156
	ds_read_b128 v[148:151], v156 offset:1024
	ds_read_b128 v[152:155], v156 offset:2048
	ds_read_b128 v[156:159], v156 offset:3072
	s_mov_b32 m0, s23
	ds_read_b128 v[160:163], v239 offset:32768
	ds_read_b128 v[164:167], v239 offset:33792
	ds_read_b128 v[168:171], v239 offset:34816
	ds_read_b128 v[172:175], v239 offset:35840
	ds_read_b128 v[176:179], v239 offset:36864
	ds_read_b128 v[180:183], v239 offset:37888
	ds_read_b128 v[184:187], v239 offset:38912
	ds_read_b128 v[188:191], v239 offset:39936
	global_load_lds_dwordx4 v216, s[58:59]
	s_mov_b32 m0, s83
	s_nop 0
	global_load_lds_dwordx4 v218, s[58:59]
	s_waitcnt vmcnt(8)
	s_waitcnt lgkmcnt(0)
	s_barrier
	s_setprio 1
	s_waitcnt lgkmcnt(0)
	v_mfma_f32_16x16x32_bf16 v[128:131], v[64:67], v[160:163], v[128:131]
	v_mfma_f32_16x16x32_bf16 v[124:127], v[136:139], v[160:163], v[124:127]
	v_mfma_f32_16x16x32_bf16 v[112:115], v[64:67], v[168:171], v[112:115]
	v_mfma_f32_16x16x32_bf16 v[104:107], v[136:139], v[168:171], v[104:107]
	v_mfma_f32_16x16x32_bf16 v[96:99], v[64:67], v[176:179], v[96:99]
	v_mfma_f32_16x16x32_bf16 v[88:91], v[136:139], v[176:179], v[88:91]
	v_mfma_f32_16x16x32_bf16 v[80:83], v[64:67], v[184:187], v[80:83]
	v_mfma_f32_16x16x32_bf16 v[72:75], v[136:139], v[184:187], v[72:75]
	v_mfma_f32_16x16x32_bf16 v[128:131], v[132:135], v[164:167], v[128:131]
	v_mfma_f32_16x16x32_bf16 v[124:127], v[140:143], v[164:167], v[124:127]
	v_mfma_f32_16x16x32_bf16 v[112:115], v[132:135], v[172:175], v[112:115]
	v_mfma_f32_16x16x32_bf16 v[104:107], v[140:143], v[172:175], v[104:107]
	v_mfma_f32_16x16x32_bf16 v[96:99], v[132:135], v[180:183], v[96:99]
	v_mfma_f32_16x16x32_bf16 v[88:91], v[140:143], v[180:183], v[88:91]
	v_mfma_f32_16x16x32_bf16 v[80:83], v[132:135], v[188:191], v[80:83]
	v_mfma_f32_16x16x32_bf16 v[72:75], v[140:143], v[188:191], v[72:75]
	s_setprio 0
	s_setprio 1
	v_mfma_f32_16x16x32_bf16 v[120:123], v[144:147], v[160:163], v[120:123]
	v_mfma_f32_16x16x32_bf16 v[116:119], v[152:155], v[160:163], v[116:119]
	v_mfma_f32_16x16x32_bf16 v[108:111], v[144:147], v[168:171], v[108:111]
	v_mfma_f32_16x16x32_bf16 v[100:103], v[152:155], v[168:171], v[100:103]
	v_mfma_f32_16x16x32_bf16 v[92:95], v[144:147], v[176:179], v[92:95]
	v_mfma_f32_16x16x32_bf16 v[84:87], v[152:155], v[176:179], v[84:87]
	v_mfma_f32_16x16x32_bf16 v[76:79], v[144:147], v[184:187], v[76:79]
	v_mfma_f32_16x16x32_bf16 v[68:71], v[152:155], v[184:187], v[68:71]
	v_mfma_f32_16x16x32_bf16 v[120:123], v[148:151], v[164:167], v[120:123]
	v_mfma_f32_16x16x32_bf16 v[116:119], v[156:159], v[164:167], v[116:119]
	v_mfma_f32_16x16x32_bf16 v[108:111], v[148:151], v[172:175], v[108:111]
	v_mfma_f32_16x16x32_bf16 v[100:103], v[156:159], v[172:175], v[100:103]
	v_mfma_f32_16x16x32_bf16 v[92:95], v[148:151], v[180:183], v[92:95]
	v_mfma_f32_16x16x32_bf16 v[84:87], v[156:159], v[180:183], v[84:87]
	v_mfma_f32_16x16x32_bf16 v[76:79], v[148:151], v[188:191], v[76:79]
	v_mfma_f32_16x16x32_bf16 v[68:71], v[156:159], v[188:191], v[68:71]
	s_setprio 0
	s_barrier
; #define PG8_STAGE(bufoff, gbase, voff) do { _Pragma("unroll") for (int _i = 0; _i < 2; ++_i) \
;         __builtin_amdgcn_global_load_lds((const unsigned*)((const char*)(gbase) + (voff)[_i]), (PG8_LAS unsigned*)(lds + (bufoff) + ldsw + _i * 8192), 16, 0, 0); } while (0)
; #define PG8_LDA(dst, b, h) do { _Pragma("unroll") for (int m = 0; m < 4; ++m) _Pragma("unroll") for (int k = 0; k < 2; ++k) dst[m][k] = *(const PG8_LAS bf16x8*)(lds + PG8_SA(b, h) + aoff + m * 2048 + k * 1024); } while (0)
; #define PG8_MMA(ai, bj, At, Bt) do { __builtin_amdgcn_s_setprio(1); _Pragma("unroll") for (int m = 0; m < 4; ++m) _Pragma("unroll") for (int n = 0; n < 2; ++n) _Pragma("unroll") for (int k = 0; k < 2; ++k) \
;         acc[ai][bj][m][n] = __builtin_amdgcn_mfma_f32_16x16x32_bf16(Bt[n][k], At[m][k], acc[ai][bj][m][n], 0, 0, 0); __builtin_amdgcn_s_setprio(0); } while (0)
; #define PG8_WAIT_V(n) asm volatile("s_waitcnt vmcnt(" #n ")" ::: "memory")
; #define PG8_WAIT_L(n) asm volatile("s_waitcnt lgkmcnt(" #n ")" ::: "memory")
; #define PG8_BAR __builtin_amdgcn_s_barrier()
; #define PG8_SCHED __builtin_amdgcn_sched_barrier(0)
; template <class Epi, class Sched, bool ALIGN_EPI = false, bool SP2 = false>
; __device__ __forceinline__ void gemm_phase(PG8_LAS unsigned char* lds, const Gemm g, const Sched& S, const Epi& E, const int wave0) {
;     ...
;             PG8_LDA(At, 1, 1); PG8_STAGE(PG8_SB(1, 0), b3, voffB); PG8_STAGE(PG8_SB(1, 1), b3 + hstep, voffB); PG8_STAGE(PG8_SA(1, 0), a3, voffA);
;             PG8_WAIT_V(8); PG8_WAIT_L(0); PG8_BAR; PG8_MMA(1, 0, At, B0); PG8_MMA(1, 1, At, B1); PG8_BAR; PG8_SCHED;
	s_add_i32 m0, s74, 0xffffff80
	ds_read_b128 v[160:163], v239 offset:49152
	ds_read_b128 v[164:167], v239 offset:50176
	ds_read_b128 v[168:171], v239 offset:51200
	ds_read_b128 v[172:175], v239 offset:52224
	ds_read_b128 v[176:179], v239 offset:53248
	ds_read_b128 v[180:183], v239 offset:54272
	ds_read_b128 v[184:187], v239 offset:55296
	ds_read_b128 v[188:191], v239 offset:56320
	global_load_lds_dwordx4 v216, s[62:63] offset:128
	s_add_i32 m0, s72, 0xffffff80
	s_nop 0
	global_load_lds_dwordx4 v218, s[62:63] offset:128
	s_mov_b32 m0, s19
	s_nop 0
	global_load_lds_dwordx4 v216, s[56:57]
	s_mov_b32 m0, s18
	s_nop 0
	global_load_lds_dwordx4 v218, s[56:57]
	s_add_i32 m0, s53, 0xffffff80
	s_nop 0
	global_load_lds_dwordx4 v216, s[60:61] offset:128
	s_add_i32 m0, s24, 0xffffff80
	s_nop 0
	global_load_lds_dwordx4 v218, s[60:61] offset:128
	s_waitcnt vmcnt(8)
	s_waitcnt lgkmcnt(0)
	s_barrier
	s_setprio 1
	s_waitcnt lgkmcnt(0)
	v_mfma_f32_16x16x32_bf16 v[60:63], v[64:67], v[160:163], v[60:63]
	v_mfma_f32_16x16x32_bf16 v[52:55], v[136:139], v[160:163], v[52:55]
	v_mfma_f32_16x16x32_bf16 v[44:47], v[64:67], v[168:171], v[44:47]
	v_mfma_f32_16x16x32_bf16 v[36:39], v[136:139], v[168:171], v[36:39]
	v_mfma_f32_16x16x32_bf16 v[28:31], v[64:67], v[176:179], v[28:31]
	v_mfma_f32_16x16x32_bf16 v[20:23], v[136:139], v[176:179], v[20:23]
	v_mfma_f32_16x16x32_bf16 v[12:15], v[64:67], v[184:187], v[12:15]
	v_mfma_f32_16x16x32_bf16 v[4:7], v[136:139], v[184:187], v[4:7]
	v_mfma_f32_16x16x32_bf16 v[60:63], v[132:135], v[164:167], v[60:63]
	v_mfma_f32_16x16x32_bf16 v[52:55], v[140:143], v[164:167], v[52:55]
	v_mfma_f32_16x16x32_bf16 v[44:47], v[132:135], v[172:175], v[44:47]
	v_mfma_f32_16x16x32_bf16 v[36:39], v[140:143], v[172:175], v[36:39]
	v_mfma_f32_16x16x32_bf16 v[28:31], v[132:135], v[180:183], v[28:31]
	v_mfma_f32_16x16x32_bf16 v[20:23], v[140:143], v[180:183], v[20:23]
	v_mfma_f32_16x16x32_bf16 v[12:15], v[132:135], v[188:191], v[12:15]
	v_mfma_f32_16x16x32_bf16 v[4:7], v[140:143], v[188:191], v[4:7]
	s_setprio 0
	s_setprio 1
	v_mfma_f32_16x16x32_bf16 v[56:59], v[144:147], v[160:163], v[56:59]
	v_mfma_f32_16x16x32_bf16 v[48:51], v[152:155], v[160:163], v[48:51]
	v_mfma_f32_16x16x32_bf16 v[40:43], v[144:147], v[168:171], v[40:43]
	v_mfma_f32_16x16x32_bf16 v[32:35], v[152:155], v[168:171], v[32:35]
	v_mfma_f32_16x16x32_bf16 v[24:27], v[144:147], v[176:179], v[24:27]
	v_mfma_f32_16x16x32_bf16 v[16:19], v[152:155], v[176:179], v[16:19]
	v_mfma_f32_16x16x32_bf16 v[8:11], v[144:147], v[184:187], v[8:11]
	v_mfma_f32_16x16x32_bf16 v[0:3], v[152:155], v[184:187], v[0:3]
	v_mfma_f32_16x16x32_bf16 v[56:59], v[148:151], v[164:167], v[56:59]
	v_mfma_f32_16x16x32_bf16 v[48:51], v[156:159], v[164:167], v[48:51]
	v_mfma_f32_16x16x32_bf16 v[40:43], v[148:151], v[172:175], v[40:43]
	v_mfma_f32_16x16x32_bf16 v[32:35], v[156:159], v[172:175], v[32:35]
	v_mfma_f32_16x16x32_bf16 v[24:27], v[148:151], v[180:183], v[24:27]
	v_mfma_f32_16x16x32_bf16 v[16:19], v[156:159], v[180:183], v[16:19]
	v_mfma_f32_16x16x32_bf16 v[8:11], v[148:151], v[188:191], v[8:11]
	v_mfma_f32_16x16x32_bf16 v[0:3], v[156:159], v[188:191], v[0:3]
	s_setprio 0
	s_barrier
	s_movk_i32 s58, 0x100
	s_andn2_b64 vcc, exec, s[54:55]
	s_mov_b64 s[56:57], -1
	s_mov_b64 s[54:55], 0
	s_cbranch_vccz .LBB0_1258
	v_readlane_b32 s66, v254, 34
	v_readlane_b32 s67, v254, 35
	s_and_b64 vcc, exec, s[66:67]
	s_cbranch_vccz .LBB0_1261
	s_barrier

; #define PG8_STAGE(bufoff, gbase, voff) do { _Pragma("unroll") for (int _i = 0; _i < 2; ++_i) \
;         __builtin_amdgcn_global_load_lds((const unsigned*)((const char*)(gbase) + (voff)[_i]), (PG8_LAS unsigned*)(lds + (bufoff) + ldsw + _i * 8192), 16, 0, 0); } while (0)
; #define PG8_LDA(dst, b, h) do { _Pragma("unroll") for (int m = 0; m < 4; ++m) _Pragma("unroll") for (int k = 0; k < 2; ++k) dst[m][k] = *(const PG8_LAS bf16x8*)(lds + PG8_SA(b, h) + aoff + m * 2048 + k * 1024); } while (0)
; #define PG8_LDB(dst, b, h) do { _Pragma("unroll") for (int n = 0; n < 2; ++n) _Pragma("unroll") for (int k = 0; k < 2; ++k) dst[n][k] = *(const PG8_LAS bf16x8*)(lds + PG8_SB(b, h) + boff + n * 2048 + k * 1024); } while (0)
; #define PG8_MMA(ai, bj, At, Bt) do { __builtin_amdgcn_s_setprio(1); _Pragma("unroll") for (int m = 0; m < 4; ++m) _Pragma("unroll") for (int n = 0; n < 2; ++n) _Pragma("unroll") for (int k = 0; k < 2; ++k) \
;         acc[ai][bj][m][n] = __builtin_amdgcn_mfma_f32_16x16x32_bf16(Bt[n][k], At[m][k], acc[ai][bj][m][n], 0, 0, 0); __builtin_amdgcn_s_setprio(0); } while (0)
; #define PG8_WAIT_V(n) asm volatile("s_waitcnt vmcnt(" #n ")" ::: "memory")
; #define PG8_WAIT_L(n) asm volatile("s_waitcnt lgkmcnt(" #n ")" ::: "memory")
; #define PG8_BAR __builtin_amdgcn_s_barrier()
; #define PG8_SCHED __builtin_amdgcn_sched_barrier(0)
; template <class Epi, class Sched, bool ALIGN_EPI = false, bool SP2 = false>
; __device__ __forceinline__ void gemm_phase(PG8_LAS unsigned char* lds, const Gemm g, const Sched& S, const Epi& E, const int wave0) {
;     ...
;             PG8_LDB(B0, 0, 0); PG8_LDB(B1, 0, 1); PG8_SCHED; PG8_LDA(At, 0, 0); PG8_STAGE(PG8_SA(1, 1), a1 + hstep, voffA);
;             PG8_WAIT_V(8); PG8_WAIT_L(0); PG8_BAR; PG8_MMA(0, 0, At, B0); PG8_MMA(0, 1, At, B1); PG8_BAR; PG8_SCHED;
;             PG8_LDA(At, 0, 1); PG8_STAGE(PG8_SB(0, 0), b2, voffB); PG8_STAGE(PG8_SB(0, 1), b2 + hstep, voffB); PG8_STAGE(PG8_SA(0, 0), a2, voffA);
;             PG8_WAIT_V(8); PG8_WAIT_L(0); PG8_BAR; PG8_MMA(1, 0, At, B0); PG8_MMA(1, 1, At, B1); PG8_BAR; PG8_SCHED;
.LBB0_1659:
	s_add_u32 s12, s10, 0x100
	s_addc_u32 s13, s11, 0
	s_add_i32 s18, 0, 0x10000
	s_cmp_eq_u32 s59, 28
	s_cselect_b32 s57, s9, s13
	s_cselect_b32 s56, s16, s12
	s_cselect_b32 s55, s17, s58
	s_cselect_b32 s54, s45, s47
	s_add_i32 s19, 0, 0x14000
	v_add_u32_e32 v140, s18, v242
	v_add_u32_e32 v156, s19, v242
	ds_read_b128 v[64:67], v140
	ds_read_b128 v[132:135], v140 offset:1024
	ds_read_b128 v[136:139], v140 offset:2048
	ds_read_b128 v[140:143], v140 offset:3072
	ds_read_b128 v[144:147], v156
	ds_read_b128 v[148:151], v156 offset:1024
	ds_read_b128 v[152:155], v156 offset:2048
	ds_read_b128 v[156:159], v156 offset:3072
	s_add_i32 m0, s33, 0xc000
	ds_read_b128 v[160:163], v243
	ds_read_b128 v[164:167], v243 offset:1024
	ds_read_b128 v[168:171], v243 offset:2048
	ds_read_b128 v[172:175], v243 offset:3072
	ds_read_b128 v[176:179], v243 offset:4096
	ds_read_b128 v[180:183], v243 offset:5120
	ds_read_b128 v[184:187], v243 offset:6144
	ds_read_b128 v[188:191], v243 offset:7168
	global_load_lds_dwordx4 v222, s[10:11]
	s_add_i32 m0, s33, 0xe000
	s_nop 0
	global_load_lds_dwordx4 v224, s[10:11]
	s_waitcnt vmcnt(8)
	s_waitcnt lgkmcnt(0)
	s_barrier
	s_setprio 1
	s_waitcnt lgkmcnt(0)
	v_mfma_f32_16x16x32_bf16 v[128:131], v[64:67], v[160:163], v[128:131]
	v_mfma_f32_16x16x32_bf16 v[124:127], v[136:139], v[160:163], v[124:127]
	v_mfma_f32_16x16x32_bf16 v[112:115], v[64:67], v[168:171], v[112:115]
	v_mfma_f32_16x16x32_bf16 v[104:107], v[136:139], v[168:171], v[104:107]
	v_mfma_f32_16x16x32_bf16 v[96:99], v[64:67], v[176:179], v[96:99]
	v_mfma_f32_16x16x32_bf16 v[88:91], v[136:139], v[176:179], v[88:91]
	v_mfma_f32_16x16x32_bf16 v[80:83], v[64:67], v[184:187], v[80:83]
	v_mfma_f32_16x16x32_bf16 v[72:75], v[136:139], v[184:187], v[72:75]
	v_mfma_f32_16x16x32_bf16 v[128:131], v[132:135], v[164:167], v[128:131]
	v_mfma_f32_16x16x32_bf16 v[124:127], v[140:143], v[164:167], v[124:127]
	v_mfma_f32_16x16x32_bf16 v[112:115], v[132:135], v[172:175], v[112:115]
	v_mfma_f32_16x16x32_bf16 v[104:107], v[140:143], v[172:175], v[104:107]
	v_mfma_f32_16x16x32_bf16 v[96:99], v[132:135], v[180:183], v[96:99]
	v_mfma_f32_16x16x32_bf16 v[88:91], v[140:143], v[180:183], v[88:91]
	v_mfma_f32_16x16x32_bf16 v[80:83], v[132:135], v[188:191], v[80:83]
	v_mfma_f32_16x16x32_bf16 v[72:75], v[140:143], v[188:191], v[72:75]
	s_setprio 0
	s_setprio 1
	v_mfma_f32_16x16x32_bf16 v[120:123], v[144:147], v[160:163], v[120:123]
	v_mfma_f32_16x16x32_bf16 v[116:119], v[152:155], v[160:163], v[116:119]
	v_mfma_f32_16x16x32_bf16 v[108:111], v[144:147], v[168:171], v[108:111]
	v_mfma_f32_16x16x32_bf16 v[100:103], v[152:155], v[168:171], v[100:103]
	v_mfma_f32_16x16x32_bf16 v[92:95], v[144:147], v[176:179], v[92:95]
	v_mfma_f32_16x16x32_bf16 v[84:87], v[152:155], v[176:179], v[84:87]
	v_mfma_f32_16x16x32_bf16 v[76:79], v[144:147], v[184:187], v[76:79]
	v_mfma_f32_16x16x32_bf16 v[68:71], v[152:155], v[184:187], v[68:71]
	v_mfma_f32_16x16x32_bf16 v[120:123], v[148:151], v[164:167], v[120:123]
	v_mfma_f32_16x16x32_bf16 v[116:119], v[156:159], v[164:167], v[116:119]
	v_mfma_f32_16x16x32_bf16 v[108:111], v[148:151], v[172:175], v[108:111]
	v_mfma_f32_16x16x32_bf16 v[100:103], v[156:159], v[172:175], v[100:103]
	v_mfma_f32_16x16x32_bf16 v[92:95], v[148:151], v[180:183], v[92:95]
	v_mfma_f32_16x16x32_bf16 v[84:87], v[156:159], v[180:183], v[84:87]
	v_mfma_f32_16x16x32_bf16 v[76:79], v[148:151], v[188:191], v[76:79]
	v_mfma_f32_16x16x32_bf16 v[68:71], v[156:159], v[188:191], v[68:71]
	s_setprio 0
	s_barrier
	s_add_i32 s10, s18, s95
	s_mov_b32 m0, s10
	ds_read_b128 v[160:163], v243 offset:16384
	ds_read_b128 v[164:167], v243 offset:17408
	ds_read_b128 v[168:171], v243 offset:18432
	ds_read_b128 v[172:175], v243 offset:19456
	ds_read_b128 v[176:179], v243 offset:20480
	ds_read_b128 v[180:183], v243 offset:21504
	ds_read_b128 v[184:187], v243 offset:22528
	ds_read_b128 v[188:191], v243 offset:23552
	global_load_lds_dwordx4 v216, s[54:55]
	s_add_i32 m0, s10, 0x2000
	s_add_u32 s10, s54, 0x80000
	s_addc_u32 s11, s55, 0
	s_add_i32 s18, s19, s95
	global_load_lds_dwordx4 v218, s[54:55]
	s_mov_b32 m0, s18
	s_nop 0
	global_load_lds_dwordx4 v216, s[10:11]
	s_add_i32 m0, s18, 0x2000
	s_nop 0
	global_load_lds_dwordx4 v218, s[10:11]
	s_mov_b32 m0, s33
	s_nop 0
	global_load_lds_dwordx4 v216, s[56:57]
	s_mov_b32 m0, s82
	s_nop 0
	global_load_lds_dwordx4 v218, s[56:57]
	s_waitcnt vmcnt(8)
	s_waitcnt lgkmcnt(0)
	s_barrier
	s_setprio 1
	s_waitcnt lgkmcnt(0)
	v_mfma_f32_16x16x32_bf16 v[60:63], v[64:67], v[160:163], v[60:63]
	v_mfma_f32_16x16x32_bf16 v[52:55], v[136:139], v[160:163], v[52:55]
	v_mfma_f32_16x16x32_bf16 v[44:47], v[64:67], v[168:171], v[44:47]
	v_mfma_f32_16x16x32_bf16 v[36:39], v[136:139], v[168:171], v[36:39]
	v_mfma_f32_16x16x32_bf16 v[28:31], v[64:67], v[176:179], v[28:31]
	v_mfma_f32_16x16x32_bf16 v[20:23], v[136:139], v[176:179], v[20:23]
	v_mfma_f32_16x16x32_bf16 v[12:15], v[64:67], v[184:187], v[12:15]
	v_mfma_f32_16x16x32_bf16 v[4:7], v[136:139], v[184:187], v[4:7]
	v_mfma_f32_16x16x32_bf16 v[60:63], v[132:135], v[164:167], v[60:63]
	v_mfma_f32_16x16x32_bf16 v[52:55], v[140:143], v[164:167], v[52:55]
	v_mfma_f32_16x16x32_bf16 v[44:47], v[132:135], v[172:175], v[44:47]
	v_mfma_f32_16x16x32_bf16 v[36:39], v[140:143], v[172:175], v[36:39]
	v_mfma_f32_16x16x32_bf16 v[28:31], v[132:135], v[180:183], v[28:31]
	v_mfma_f32_16x16x32_bf16 v[20:23], v[140:143], v[180:183], v[20:23]
	v_mfma_f32_16x16x32_bf16 v[12:15], v[132:135], v[188:191], v[12:15]
	v_mfma_f32_16x16x32_bf16 v[4:7], v[140:143], v[188:191], v[4:7]
	s_setprio 0
	s_setprio 1
	v_mfma_f32_16x16x32_bf16 v[56:59], v[144:147], v[160:163], v[56:59]
	v_mfma_f32_16x16x32_bf16 v[48:51], v[152:155], v[160:163], v[48:51]
	v_mfma_f32_16x16x32_bf16 v[40:43], v[144:147], v[168:171], v[40:43]
	v_mfma_f32_16x16x32_bf16 v[32:35], v[152:155], v[168:171], v[32:35]
	v_mfma_f32_16x16x32_bf16 v[24:27], v[144:147], v[176:179], v[24:27]
	v_mfma_f32_16x16x32_bf16 v[16:19], v[152:155], v[176:179], v[16:19]
	v_mfma_f32_16x16x32_bf16 v[8:11], v[144:147], v[184:187], v[8:11]
	v_mfma_f32_16x16x32_bf16 v[0:3], v[152:155], v[184:187], v[0:3]
	v_mfma_f32_16x16x32_bf16 v[56:59], v[148:151], v[164:167], v[56:59]
	v_mfma_f32_16x16x32_bf16 v[48:51], v[156:159], v[164:167], v[48:51]
	v_mfma_f32_16x16x32_bf16 v[40:43], v[148:151], v[172:175], v[40:43]
	v_mfma_f32_16x16x32_bf16 v[32:35], v[156:159], v[172:175], v[32:35]
	v_mfma_f32_16x16x32_bf16 v[24:27], v[148:151], v[180:183], v[24:27]
	v_mfma_f32_16x16x32_bf16 v[16:19], v[156:159], v[180:183], v[16:19]
	v_mfma_f32_16x16x32_bf16 v[8:11], v[148:151], v[188:191], v[8:11]
	v_mfma_f32_16x16x32_bf16 v[0:3], v[156:159], v[188:191], v[0:3]
	s_setprio 0
	s_barrier
; #define PG8_STAGE(bufoff, gbase, voff) do { _Pragma("unroll") for (int _i = 0; _i < 2; ++_i) \
;         __builtin_amdgcn_global_load_lds((const unsigned*)((const char*)(gbase) + (voff)[_i]), (PG8_LAS unsigned*)(lds + (bufoff) + ldsw + _i * 8192), 16, 0, 0); } while (0)
; #define PG8_LDA(dst, b, h) do { _Pragma("unroll") for (int m = 0; m < 4; ++m) _Pragma("unroll") for (int k = 0; k < 2; ++k) dst[m][k] = *(const PG8_LAS bf16x8*)(lds + PG8_SA(b, h) + aoff + m * 2048 + k * 1024); } while (0)
; #define PG8_LDB(dst, b, h) do { _Pragma("unroll") for (int n = 0; n < 2; ++n) _Pragma("unroll") for (int k = 0; k < 2; ++k) dst[n][k] = *(const PG8_LAS bf16x8*)(lds + PG8_SB(b, h) + boff + n * 2048 + k * 1024); } while (0)
; #define PG8_MMA(ai, bj, At, Bt) do { __builtin_amdgcn_s_setprio(1); _Pragma("unroll") for (int m = 0; m < 4; ++m) _Pragma("unroll") for (int n = 0; n < 2; ++n) _Pragma("unroll") for (int k = 0; k < 2; ++k) \
;         acc[ai][bj][m][n] = __builtin_amdgcn_mfma_f32_16x16x32_bf16(Bt[n][k], At[m][k], acc[ai][bj][m][n], 0, 0, 0); __builtin_amdgcn_s_setprio(0); } while (0)
; #define PG8_WAIT_V(n) asm volatile("s_waitcnt vmcnt(" #n ")" ::: "memory")
; #define PG8_WAIT_L(n) asm volatile("s_waitcnt lgkmcnt(" #n ")" ::: "memory")
; #define PG8_BAR __builtin_amdgcn_s_barrier()
; #define PG8_SCHED __builtin_amdgcn_sched_barrier(0)
; template <class Epi, class Sched, bool ALIGN_EPI = false, bool SP2 = false>
; __device__ __forceinline__ void gemm_phase(PG8_LAS unsigned char* lds, const Gemm g, const Sched& S, const Epi& E, const int wave0) {
;     ...
;             PG8_LDB(B0, 1, 0); PG8_LDB(B1, 1, 1); PG8_SCHED; PG8_LDA(At, 1, 0); PG8_STAGE(PG8_SA(0, 1), a2 + hstep, voffA);
;             PG8_WAIT_V(8); PG8_WAIT_L(0); PG8_BAR; PG8_MMA(0, 0, At, B0); PG8_MMA(0, 1, At, B1); PG8_BAR; PG8_SCHED;
;             PG8_LDA(At, 1, 1); PG8_STAGE(PG8_SB(1, 0), b3, voffB); PG8_STAGE(PG8_SB(1, 1), b3 + hstep, voffB); PG8_STAGE(PG8_SA(1, 0), a3, voffA);
;             PG8_WAIT_V(8); PG8_WAIT_L(0); PG8_BAR; PG8_MMA(1, 0, At, B0); PG8_MMA(1, 1, At, B1); PG8_BAR; PG8_SCHED;
	s_add_i32 s18, 0, 0x18000
	s_add_i32 s19, 0, 0x1c000
	v_add_u32_e32 v140, s18, v242
	v_add_u32_e32 v156, s19, v242
	ds_read_b128 v[64:67], v140
	ds_read_b128 v[132:135], v140 offset:1024
	ds_read_b128 v[136:139], v140 offset:2048
	ds_read_b128 v[140:143], v140 offset:3072
	ds_read_b128 v[144:147], v156
	ds_read_b128 v[148:151], v156 offset:1024
	ds_read_b128 v[152:155], v156 offset:2048
	ds_read_b128 v[156:159], v156 offset:3072
	s_add_u32 s10, s56, 0x80000
	s_addc_u32 s11, s57, 0
	s_mov_b32 m0, s22
	ds_read_b128 v[160:163], v243 offset:32768
	ds_read_b128 v[164:167], v243 offset:33792
	ds_read_b128 v[168:171], v243 offset:34816
	ds_read_b128 v[172:175], v243 offset:35840
	ds_read_b128 v[176:179], v243 offset:36864
	ds_read_b128 v[180:183], v243 offset:37888
	ds_read_b128 v[184:187], v243 offset:38912
	ds_read_b128 v[188:191], v243 offset:39936
	global_load_lds_dwordx4 v216, s[10:11]
	s_mov_b32 m0, s83
	s_nop 0
	global_load_lds_dwordx4 v218, s[10:11]
	s_waitcnt vmcnt(8)
	s_waitcnt lgkmcnt(0)
	s_barrier
	s_setprio 1
	s_waitcnt lgkmcnt(0)
	v_mfma_f32_16x16x32_bf16 v[128:131], v[64:67], v[160:163], v[128:131]
	v_mfma_f32_16x16x32_bf16 v[124:127], v[136:139], v[160:163], v[124:127]
	v_mfma_f32_16x16x32_bf16 v[112:115], v[64:67], v[168:171], v[112:115]
	v_mfma_f32_16x16x32_bf16 v[104:107], v[136:139], v[168:171], v[104:107]
	v_mfma_f32_16x16x32_bf16 v[96:99], v[64:67], v[176:179], v[96:99]
	v_mfma_f32_16x16x32_bf16 v[88:91], v[136:139], v[176:179], v[88:91]
	v_mfma_f32_16x16x32_bf16 v[80:83], v[64:67], v[184:187], v[80:83]
	v_mfma_f32_16x16x32_bf16 v[72:75], v[136:139], v[184:187], v[72:75]
	v_mfma_f32_16x16x32_bf16 v[128:131], v[132:135], v[164:167], v[128:131]
	v_mfma_f32_16x16x32_bf16 v[124:127], v[140:143], v[164:167], v[124:127]
	v_mfma_f32_16x16x32_bf16 v[112:115], v[132:135], v[172:175], v[112:115]
	v_mfma_f32_16x16x32_bf16 v[104:107], v[140:143], v[172:175], v[104:107]
	v_mfma_f32_16x16x32_bf16 v[96:99], v[132:135], v[180:183], v[96:99]
	v_mfma_f32_16x16x32_bf16 v[88:91], v[140:143], v[180:183], v[88:91]
	v_mfma_f32_16x16x32_bf16 v[80:83], v[132:135], v[188:191], v[80:83]
	v_mfma_f32_16x16x32_bf16 v[72:75], v[140:143], v[188:191], v[72:75]
	s_setprio 0
	s_setprio 1
	v_mfma_f32_16x16x32_bf16 v[120:123], v[144:147], v[160:163], v[120:123]
	v_mfma_f32_16x16x32_bf16 v[116:119], v[152:155], v[160:163], v[116:119]
	v_mfma_f32_16x16x32_bf16 v[108:111], v[144:147], v[168:171], v[108:111]
	v_mfma_f32_16x16x32_bf16 v[100:103], v[152:155], v[168:171], v[100:103]
	v_mfma_f32_16x16x32_bf16 v[92:95], v[144:147], v[176:179], v[92:95]
	v_mfma_f32_16x16x32_bf16 v[84:87], v[152:155], v[176:179], v[84:87]
	v_mfma_f32_16x16x32_bf16 v[76:79], v[144:147], v[184:187], v[76:79]
	v_mfma_f32_16x16x32_bf16 v[68:71], v[152:155], v[184:187], v[68:71]
	v_mfma_f32_16x16x32_bf16 v[120:123], v[148:151], v[164:167], v[120:123]
	v_mfma_f32_16x16x32_bf16 v[116:119], v[156:159], v[164:167], v[116:119]
	v_mfma_f32_16x16x32_bf16 v[108:111], v[148:151], v[172:175], v[108:111]
	v_mfma_f32_16x16x32_bf16 v[100:103], v[156:159], v[172:175], v[100:103]
	v_mfma_f32_16x16x32_bf16 v[92:95], v[148:151], v[180:183], v[92:95]
	v_mfma_f32_16x16x32_bf16 v[84:87], v[156:159], v[180:183], v[84:87]
	v_mfma_f32_16x16x32_bf16 v[76:79], v[148:151], v[188:191], v[76:79]
	v_mfma_f32_16x16x32_bf16 v[68:71], v[156:159], v[188:191], v[68:71]
	s_setprio 0
	s_barrier
	s_add_i32 s10, s18, s95
	s_add_i32 m0, s10, 0xffffff80
	ds_read_b128 v[160:163], v243 offset:49152
	ds_read_b128 v[164:167], v243 offset:50176
	ds_read_b128 v[168:171], v243 offset:51200
	ds_read_b128 v[172:175], v243 offset:52224
	ds_read_b128 v[176:179], v243 offset:53248
	ds_read_b128 v[180:183], v243 offset:54272
	ds_read_b128 v[184:187], v243 offset:55296
	ds_read_b128 v[188:191], v243 offset:56320
	global_load_lds_dwordx4 v216, s[54:55] offset:128
	s_add_i32 m0, s10, 0x1f80
	s_add_u32 s10, s54, 0x80080
	s_addc_u32 s11, s55, 0
	s_add_i32 s18, s19, s95
	global_load_lds_dwordx4 v218, s[54:55] offset:128
	s_mov_b32 m0, s18
	s_nop 0
	global_load_lds_dwordx4 v216, s[10:11]
	s_add_i32 m0, s18, 0x2000
	s_nop 0
	global_load_lds_dwordx4 v218, s[10:11]
	s_add_i32 m0, s23, 0xffffff80
	s_nop 0
	global_load_lds_dwordx4 v216, s[56:57] offset:128
	s_add_i32 m0, s24, 0xffffff80
	s_nop 0
	global_load_lds_dwordx4 v218, s[56:57] offset:128
	s_waitcnt vmcnt(8)
	s_waitcnt lgkmcnt(0)
	s_barrier
	s_setprio 1
	s_waitcnt lgkmcnt(0)
	v_mfma_f32_16x16x32_bf16 v[60:63], v[64:67], v[160:163], v[60:63]
	v_mfma_f32_16x16x32_bf16 v[52:55], v[136:139], v[160:163], v[52:55]
	v_mfma_f32_16x16x32_bf16 v[44:47], v[64:67], v[168:171], v[44:47]
	v_mfma_f32_16x16x32_bf16 v[36:39], v[136:139], v[168:171], v[36:39]
	v_mfma_f32_16x16x32_bf16 v[28:31], v[64:67], v[176:179], v[28:31]
	v_mfma_f32_16x16x32_bf16 v[20:23], v[136:139], v[176:179], v[20:23]
	v_mfma_f32_16x16x32_bf16 v[12:15], v[64:67], v[184:187], v[12:15]
	v_mfma_f32_16x16x32_bf16 v[4:7], v[136:139], v[184:187], v[4:7]
	v_mfma_f32_16x16x32_bf16 v[60:63], v[132:135], v[164:167], v[60:63]
	v_mfma_f32_16x16x32_bf16 v[52:55], v[140:143], v[164:167], v[52:55]
	v_mfma_f32_16x16x32_bf16 v[44:47], v[132:135], v[172:175], v[44:47]
	v_mfma_f32_16x16x32_bf16 v[36:39], v[140:143], v[172:175], v[36:39]
	v_mfma_f32_16x16x32_bf16 v[28:31], v[132:135], v[180:183], v[28:31]
	v_mfma_f32_16x16x32_bf16 v[20:23], v[140:143], v[180:183], v[20:23]
	v_mfma_f32_16x16x32_bf16 v[12:15], v[132:135], v[188:191], v[12:15]
	v_mfma_f32_16x16x32_bf16 v[4:7], v[140:143], v[188:191], v[4:7]
	s_setprio 0
	s_setprio 1
	v_mfma_f32_16x16x32_bf16 v[56:59], v[144:147], v[160:163], v[56:59]
	v_mfma_f32_16x16x32_bf16 v[48:51], v[152:155], v[160:163], v[48:51]
	v_mfma_f32_16x16x32_bf16 v[40:43], v[144:147], v[168:171], v[40:43]
	v_mfma_f32_16x16x32_bf16 v[32:35], v[152:155], v[168:171], v[32:35]
	v_mfma_f32_16x16x32_bf16 v[24:27], v[144:147], v[176:179], v[24:27]
	v_mfma_f32_16x16x32_bf16 v[16:19], v[152:155], v[176:179], v[16:19]
	v_mfma_f32_16x16x32_bf16 v[8:11], v[144:147], v[184:187], v[8:11]
	v_mfma_f32_16x16x32_bf16 v[0:3], v[152:155], v[184:187], v[0:3]
	v_mfma_f32_16x16x32_bf16 v[56:59], v[148:151], v[164:167], v[56:59]
	v_mfma_f32_16x16x32_bf16 v[48:51], v[156:159], v[164:167], v[48:51]
	v_mfma_f32_16x16x32_bf16 v[40:43], v[148:151], v[172:175], v[40:43]
	v_mfma_f32_16x16x32_bf16 v[32:35], v[156:159], v[172:175], v[32:35]
	v_mfma_f32_16x16x32_bf16 v[24:27], v[148:151], v[180:183], v[24:27]
	v_mfma_f32_16x16x32_bf16 v[16:19], v[156:159], v[180:183], v[16:19]
	v_mfma_f32_16x16x32_bf16 v[8:11], v[148:151], v[188:191], v[8:11]
	v_mfma_f32_16x16x32_bf16 v[0:3], v[156:159], v[188:191], v[0:3]
	s_setprio 0
	s_barrier
	s_add_i32 s59, s59, 2
	s_add_u32 s47, s47, 0x100
	s_addc_u32 s58, s58, 0
	s_cmp_gt_u32 s59, 29
	s_mov_b64 s[10:11], s[12:13]
	s_cbranch_scc0 .LBB0_1659
	s_and_b64 vcc, exec, s[66:67]
	s_cbranch_vccz .LBB0_1662
	s_barrier
